# GLA passes: the issue slots left where the bf16 rounding-bit computation was removed are dropped (263 of 266; each removal checked against the hazard tables)
# baseline (speedup 1.0000x reference)
.LBB0_184:
	s_or_b64 exec, exec, s[6:7]
	v_lshlrev_b64 v[50:51], 1, v[46:47]
	v_lshl_add_u64 v[46:47], s[14:15], 0, v[50:51]
	global_load_dwordx4 v[46:49], v[46:47], off
	s_waitcnt vmcnt(0)
	v_mov_b32_e32 v45, v13
	v_mov_b32_e32 v66, v25
	v_mov_b32_e32 v71, v21
	v_mov_b32_e32 v74, v29
	v_lshlrev_b32_e32 v52, 16, v40
	v_lshlrev_b32_e32 v53, 16, v41
	v_mov_b32_e32 v25, v26
	v_mov_b32_e32 v29, v30
	v_mov_b32_e32 v67, v5
	v_mov_b32_e32 v68, v17
	v_lshlrev_b32_e32 v55, 16, v33
	v_lshlrev_b32_e32 v54, 16, v32
	v_and_b32_e32 v59, 0xffff0000, v41
	v_and_b32_e32 v58, 0xffff0000, v40
	v_lshlrev_b32_e32 v40, 16, v42
	v_and_b32_e32 v65, 0xffff0000, v43
	v_and_b32_e32 v64, 0xffff0000, v42
	v_lshlrev_b32_e32 v41, 16, v43
	v_mov_b32_e32 v17, v18
	v_mov_b32_e32 v13, v14
	v_mov_b32_e32 v21, v22
	v_lshl_add_u64 v[42:43], s[24:25], 0, v[50:51]
	v_pk_fma_f32 v[50:51], v[24:25], v[52:53], v[28:29]
	v_mov_b32_e32 v26, v66
	v_mov_b32_e32 v30, v74
	v_mov_b32_e32 v14, v45
	v_mov_b32_e32 v22, v71
	v_mov_b32_e32 v69, v1
	v_mov_b32_e32 v70, v9
	v_and_b32_e32 v33, 0xffff0000, v33
	v_and_b32_e32 v32, 0xffff0000, v32
	v_lshlrev_b32_e32 v61, 16, v35
	v_lshlrev_b32_e32 v60, 16, v34
	v_and_b32_e32 v35, 0xffff0000, v35
	v_and_b32_e32 v34, 0xffff0000, v34
	v_mov_b32_e32 v5, v6
	v_mov_b32_e32 v18, v68
	v_mov_b32_e32 v6, v67
	v_pk_fma_f32 v[50:51], v[16:17], v[54:55], v[50:51]
	v_pk_fma_f32 v[52:53], v[26:27], v[58:59], v[30:31]
	v_pk_fma_f32 v[54:55], v[14:15], v[64:65], v[22:23]
	v_lshlrev_b32_e32 v57, 16, v37
	v_lshlrev_b32_e32 v56, 16, v36
	v_and_b32_e32 v37, 0xffff0000, v37
	v_and_b32_e32 v36, 0xffff0000, v36
	v_lshlrev_b32_e32 v63, 16, v39
	v_lshlrev_b32_e32 v62, 16, v38
	v_and_b32_e32 v39, 0xffff0000, v39
	v_and_b32_e32 v38, 0xffff0000, v38
	v_mov_b32_e32 v9, v10
	v_mov_b32_e32 v1, v2
	v_mov_b32_e32 v10, v70
	v_pk_fma_f32 v[40:41], v[12:13], v[40:41], v[20:21]
	v_mov_b32_e32 v2, v69
	v_pk_fma_f32 v[32:33], v[18:19], v[32:33], v[52:53]
	v_pk_fma_f32 v[34:35], v[6:7], v[34:35], v[54:55]
	v_pk_fma_f32 v[40:41], v[4:5], v[60:61], v[40:41]
	v_pk_fma_f32 v[32:33], v[10:11], v[36:37], v[32:33]
	v_pk_fma_f32 v[34:35], v[2:3], v[38:39], v[34:35]
	v_pk_fma_f32 v[50:51], v[8:9], v[56:57], v[50:51]
	v_pk_fma_f32 v[40:41], v[0:1], v[62:63], v[40:41]
	v_add_u32_e32 v74, 2, v44
	v_and_b32_e32 v39, 0xffff0000, v47
	v_and_b32_e32 v38, 0xffff0000, v46
	v_lshlrev_b32_e32 v37, 16, v47
	v_lshlrev_b32_e32 v36, 16, v46
	v_lshlrev_b32_e32 v47, 16, v49
	v_lshlrev_b32_e32 v46, 16, v48
	v_pk_mul_f32 v[32:33], v[32:33], v[38:39]
	v_pk_mul_f32 v[36:37], v[50:51], v[36:37]
	v_pk_mul_f32 v[38:39], v[40:41], v[46:47]
	v_cvt_pk_bf16_f32 v33, v33, v33
	v_cvt_pk_bf16_f32 v32, v32, v32
	v_and_b32_e32 v49, 0xffff0000, v49
	v_and_b32_e32 v48, 0xffff0000, v48
	v_cvt_pk_bf16_f32 v36, v36, v36
	v_cvt_pk_bf16_f32 v37, v37, v37
	v_and_b32_e32 v33, 0xffff0000, v33
	v_and_b32_e32 v32, 0xffff0000, v32
	v_pk_mul_f32 v[34:35], v[34:35], v[48:49]
	v_or_b32_sdwa v33, v33, v37 dst_sel:DWORD dst_unused:UNUSED_PAD src0_sel:DWORD src1_sel:WORD_1
	v_or_b32_sdwa v32, v32, v36 dst_sel:DWORD dst_unused:UNUSED_PAD src0_sel:DWORD src1_sel:WORD_1
	v_cvt_pk_bf16_f32 v37, v38, v38
	v_cvt_pk_bf16_f32 v36, v39, v39
	v_cvt_pk_bf16_f32 v35, v35, v35
	v_cvt_pk_bf16_f32 v34, v34, v34
	v_and_b32_e32 v35, 0xffff0000, v35
	v_and_b32_e32 v34, 0xffff0000, v34
	v_lshlrev_b64 v[46:47], 10, v[74:75]
	v_or_b32_sdwa v35, v35, v36 dst_sel:DWORD dst_unused:UNUSED_PAD src0_sel:DWORD src1_sel:WORD_1
	v_or_b32_sdwa v34, v34, v37 dst_sel:DWORD dst_unused:UNUSED_PAD src0_sel:DWORD src1_sel:WORD_1
	v_or_b32_e32 v46, v46, v72
	global_store_dwordx4 v[42:43], v[32:35], off
	v_lshl_add_u64 v[48:49], v[46:47], 1, s[12:13]
	global_load_dwordx4 v[32:35], v[48:49], off
	v_and_b32_e32 v37, 0x1fff, v74
	v_mov_b32_e32 v36, 0
	v_cmp_ne_u32_e32 vcc, 0, v37
	v_mov_b32_e32 v42, 0
	v_mov_b32_e32 v43, 0
	v_mov_b32_e32 v40, 0
	v_mov_b32_e32 v41, 0
	s_and_saveexec_b64 s[6:7], vcc
	s_cbranch_execz .LBB0_186
	global_load_dwordx4 v[40:43], v[48:49], off offset:-2048

.LBB0_188:
	s_or_b64 exec, exec, s[6:7]
	v_lshlrev_b64 v[46:47], 1, v[46:47]
	v_lshl_add_u64 v[48:49], s[14:15], 0, v[46:47]
	global_load_dwordx4 v[48:51], v[48:49], off
	s_waitcnt vmcnt(1)
	v_lshlrev_b32_e32 v52, 16, v40
	v_and_b32_e32 v59, 0xffff0000, v41
	v_and_b32_e32 v58, 0xffff0000, v40
	v_lshlrev_b32_e32 v53, 16, v41
	v_lshlrev_b32_e32 v40, 16, v42
	v_and_b32_e32 v65, 0xffff0000, v43
	v_and_b32_e32 v64, 0xffff0000, v42
	v_lshlrev_b32_e32 v41, 16, v43
	v_lshlrev_b32_e32 v55, 16, v33
	v_lshlrev_b32_e32 v54, 16, v32
	v_and_b32_e32 v33, 0xffff0000, v33
	v_and_b32_e32 v32, 0xffff0000, v32
	v_lshlrev_b32_e32 v61, 16, v35
	v_lshlrev_b32_e32 v60, 16, v34
	v_and_b32_e32 v35, 0xffff0000, v35
	v_and_b32_e32 v34, 0xffff0000, v34
	v_pk_fma_f32 v[58:59], v[26:27], v[58:59], v[30:31]
	v_pk_fma_f32 v[40:41], v[12:13], v[40:41], v[20:21]
	v_pk_fma_f32 v[64:65], v[14:15], v[64:65], v[22:23]
	v_lshlrev_b32_e32 v57, 16, v37
	v_lshlrev_b32_e32 v56, 16, v36
	v_and_b32_e32 v37, 0xffff0000, v37
	v_and_b32_e32 v36, 0xffff0000, v36
	v_lshlrev_b32_e32 v63, 16, v39
	v_lshlrev_b32_e32 v62, 16, v38
	v_and_b32_e32 v39, 0xffff0000, v39
	v_and_b32_e32 v38, 0xffff0000, v38
	v_pk_fma_f32 v[52:53], v[24:25], v[52:53], v[28:29]
	v_pk_fma_f32 v[32:33], v[18:19], v[32:33], v[58:59]
	v_pk_fma_f32 v[40:41], v[4:5], v[60:61], v[40:41]
	v_pk_fma_f32 v[34:35], v[6:7], v[34:35], v[64:65]
	v_pk_fma_f32 v[52:53], v[16:17], v[54:55], v[52:53]
	v_pk_fma_f32 v[32:33], v[10:11], v[36:37], v[32:33]
	v_pk_fma_f32 v[36:37], v[0:1], v[62:63], v[40:41]
	v_pk_fma_f32 v[34:35], v[2:3], v[38:39], v[34:35]
	v_pk_fma_f32 v[52:53], v[8:9], v[56:57], v[52:53]
	v_add_u32_e32 v74, 4, v44
	v_lshl_add_u64 v[42:43], s[24:25], 0, v[46:47]
	v_lshlrev_b64 v[46:47], 10, v[74:75]
	v_or_b32_e32 v46, v46, v72
	s_waitcnt vmcnt(0)
	v_lshlrev_b32_e32 v39, 16, v49
	v_lshlrev_b32_e32 v38, 16, v48
	v_and_b32_e32 v41, 0xffff0000, v49
	v_and_b32_e32 v40, 0xffff0000, v48
	v_lshlrev_b32_e32 v49, 16, v51
	v_lshlrev_b32_e32 v48, 16, v50
	v_and_b32_e32 v51, 0xffff0000, v51
	v_and_b32_e32 v50, 0xffff0000, v50
	v_pk_mul_f32 v[32:33], v[32:33], v[40:41]
	v_pk_mul_f32 v[34:35], v[34:35], v[50:51]
	v_pk_mul_f32 v[38:39], v[52:53], v[38:39]
	v_pk_mul_f32 v[36:37], v[36:37], v[48:49]
	v_cvt_pk_bf16_f32 v33, v33, v33
	v_cvt_pk_bf16_f32 v32, v32, v32
	v_cvt_pk_bf16_f32 v35, v35, v35
	v_cvt_pk_bf16_f32 v34, v34, v34
	v_cvt_pk_bf16_f32 v38, v38, v38
	v_cvt_pk_bf16_f32 v39, v39, v39
	v_cvt_pk_bf16_f32 v36, v36, v36
	v_cvt_pk_bf16_f32 v37, v37, v37
	v_and_b32_e32 v33, 0xffff0000, v33
	v_and_b32_e32 v32, 0xffff0000, v32
	v_and_b32_e32 v35, 0xffff0000, v35
	v_and_b32_e32 v34, 0xffff0000, v34
	v_or_b32_sdwa v33, v33, v39 dst_sel:DWORD dst_unused:UNUSED_PAD src0_sel:DWORD src1_sel:WORD_1
	v_or_b32_sdwa v32, v32, v38 dst_sel:DWORD dst_unused:UNUSED_PAD src0_sel:DWORD src1_sel:WORD_1
	v_or_b32_sdwa v35, v35, v37 dst_sel:DWORD dst_unused:UNUSED_PAD src0_sel:DWORD src1_sel:WORD_1
	v_or_b32_sdwa v34, v34, v36 dst_sel:DWORD dst_unused:UNUSED_PAD src0_sel:DWORD src1_sel:WORD_1
	global_store_dwordx4 v[42:43], v[32:35], off
	v_lshl_add_u64 v[48:49], v[46:47], 1, s[12:13]
	global_load_dwordx4 v[32:35], v[48:49], off
	v_and_b32_e32 v37, 0x1fff, v74
	v_mov_b32_e32 v36, 0
	v_cmp_ne_u32_e32 vcc, 0, v37
	v_mov_b32_e32 v42, 0
	v_mov_b32_e32 v43, 0
	v_mov_b32_e32 v40, 0
	v_mov_b32_e32 v41, 0
	s_and_saveexec_b64 s[6:7], vcc
	s_cbranch_execz .LBB0_190
	global_load_dwordx4 v[40:43], v[48:49], off offset:-2048

.LBB0_192:
	s_or_b64 exec, exec, s[6:7]
	v_lshlrev_b64 v[50:51], 1, v[46:47]
	v_lshl_add_u64 v[46:47], s[14:15], 0, v[50:51]
	global_load_dwordx4 v[46:49], v[46:47], off
	s_waitcnt vmcnt(1)
	v_lshlrev_b32_e32 v52, 16, v40
	v_and_b32_e32 v59, 0xffff0000, v41
	v_and_b32_e32 v58, 0xffff0000, v40
	v_lshlrev_b32_e32 v53, 16, v41
	v_lshlrev_b32_e32 v40, 16, v42
	v_and_b32_e32 v65, 0xffff0000, v43
	v_and_b32_e32 v64, 0xffff0000, v42
	v_lshlrev_b32_e32 v41, 16, v43
	v_lshlrev_b32_e32 v55, 16, v33
	v_lshlrev_b32_e32 v54, 16, v32
	v_and_b32_e32 v33, 0xffff0000, v33
	v_and_b32_e32 v32, 0xffff0000, v32
	v_lshlrev_b32_e32 v61, 16, v35
	v_lshlrev_b32_e32 v60, 16, v34
	v_and_b32_e32 v35, 0xffff0000, v35
	v_and_b32_e32 v34, 0xffff0000, v34
	v_lshl_add_u64 v[42:43], s[24:25], 0, v[50:51]
	v_pk_fma_f32 v[50:51], v[24:25], v[52:53], v[28:29]
	v_pk_fma_f32 v[52:53], v[26:27], v[58:59], v[30:31]
	v_pk_fma_f32 v[40:41], v[12:13], v[40:41], v[20:21]
	v_pk_fma_f32 v[58:59], v[14:15], v[64:65], v[22:23]
	v_lshlrev_b32_e32 v57, 16, v37
	v_lshlrev_b32_e32 v56, 16, v36
	v_and_b32_e32 v37, 0xffff0000, v37
	v_and_b32_e32 v36, 0xffff0000, v36
	v_lshlrev_b32_e32 v63, 16, v39
	v_lshlrev_b32_e32 v62, 16, v38
	v_and_b32_e32 v39, 0xffff0000, v39
	v_and_b32_e32 v38, 0xffff0000, v38
	v_pk_fma_f32 v[32:33], v[18:19], v[32:33], v[52:53]
	v_pk_fma_f32 v[40:41], v[4:5], v[60:61], v[40:41]
	v_pk_fma_f32 v[34:35], v[6:7], v[34:35], v[58:59]
	v_pk_fma_f32 v[50:51], v[16:17], v[54:55], v[50:51]
	v_pk_fma_f32 v[32:33], v[10:11], v[36:37], v[32:33]
	v_pk_fma_f32 v[36:37], v[0:1], v[62:63], v[40:41]
	v_pk_fma_f32 v[34:35], v[2:3], v[38:39], v[34:35]
	v_pk_fma_f32 v[50:51], v[8:9], v[56:57], v[50:51]
	v_add_u32_e32 v74, 6, v44
	v_lshlrev_b64 v[44:45], 10, v[74:75]
	v_or_b32_e32 v44, v44, v72
	s_waitcnt vmcnt(0)
	v_lshlrev_b32_e32 v39, 16, v47
	v_lshlrev_b32_e32 v38, 16, v46
	v_and_b32_e32 v41, 0xffff0000, v47
	v_and_b32_e32 v40, 0xffff0000, v46
	v_lshlrev_b32_e32 v47, 16, v49
	v_lshlrev_b32_e32 v46, 16, v48
	v_and_b32_e32 v49, 0xffff0000, v49
	v_and_b32_e32 v48, 0xffff0000, v48
	v_pk_mul_f32 v[32:33], v[32:33], v[40:41]
	v_pk_mul_f32 v[34:35], v[34:35], v[48:49]
	v_pk_mul_f32 v[38:39], v[50:51], v[38:39]
	v_pk_mul_f32 v[36:37], v[36:37], v[46:47]
	v_cvt_pk_bf16_f32 v33, v33, v33
	v_cvt_pk_bf16_f32 v32, v32, v32
	v_cvt_pk_bf16_f32 v35, v35, v35
	v_cvt_pk_bf16_f32 v34, v34, v34
	v_cvt_pk_bf16_f32 v38, v38, v38
	v_cvt_pk_bf16_f32 v39, v39, v39
	v_cvt_pk_bf16_f32 v36, v36, v36
	v_cvt_pk_bf16_f32 v37, v37, v37
	v_and_b32_e32 v33, 0xffff0000, v33
	v_and_b32_e32 v32, 0xffff0000, v32
	v_and_b32_e32 v35, 0xffff0000, v35
	v_and_b32_e32 v34, 0xffff0000, v34
	v_or_b32_sdwa v33, v33, v39 dst_sel:DWORD dst_unused:UNUSED_PAD src0_sel:DWORD src1_sel:WORD_1
	v_or_b32_sdwa v32, v32, v38 dst_sel:DWORD dst_unused:UNUSED_PAD src0_sel:DWORD src1_sel:WORD_1
	v_or_b32_sdwa v35, v35, v37 dst_sel:DWORD dst_unused:UNUSED_PAD src0_sel:DWORD src1_sel:WORD_1
	v_or_b32_sdwa v34, v34, v36 dst_sel:DWORD dst_unused:UNUSED_PAD src0_sel:DWORD src1_sel:WORD_1
	global_store_dwordx4 v[42:43], v[32:35], off
	v_lshl_add_u64 v[46:47], v[44:45], 1, s[12:13]
	global_load_dwordx4 v[32:35], v[46:47], off
	v_and_b32_e32 v37, 0x1fff, v74
	v_mov_b32_e32 v36, 0
	v_cmp_ne_u32_e32 vcc, 0, v37
	v_mov_b32_e32 v42, 0
	v_mov_b32_e32 v43, 0
	v_mov_b32_e32 v40, 0
	v_mov_b32_e32 v41, 0
	s_and_saveexec_b64 s[6:7], vcc
	s_cbranch_execz .LBB0_194
	global_load_dwordx4 v[40:43], v[46:47], off offset:-2048

.LBB0_196:
	s_or_b64 exec, exec, s[6:7]
	v_lshlrev_b64 v[48:49], 1, v[44:45]
	v_lshl_add_u64 v[44:45], s[14:15], 0, v[48:49]
	global_load_dwordx4 v[44:47], v[44:45], off
	s_waitcnt vmcnt(1)
	v_lshlrev_b32_e32 v50, 16, v40
	v_and_b32_e32 v57, 0xffff0000, v41
	v_and_b32_e32 v56, 0xffff0000, v40
	v_lshlrev_b32_e32 v51, 16, v41
	v_lshlrev_b32_e32 v40, 16, v42
	v_and_b32_e32 v63, 0xffff0000, v43
	v_and_b32_e32 v62, 0xffff0000, v42
	v_lshlrev_b32_e32 v41, 16, v43
	v_lshlrev_b32_e32 v53, 16, v33
	v_lshlrev_b32_e32 v52, 16, v32
	v_and_b32_e32 v33, 0xffff0000, v33
	v_and_b32_e32 v32, 0xffff0000, v32
	v_lshlrev_b32_e32 v59, 16, v35
	v_lshlrev_b32_e32 v58, 16, v34
	v_and_b32_e32 v35, 0xffff0000, v35
	v_and_b32_e32 v34, 0xffff0000, v34
	v_pk_fma_f32 v[24:25], v[24:25], v[50:51], v[28:29]
	v_pk_fma_f32 v[26:27], v[26:27], v[56:57], v[30:31]
	v_pk_fma_f32 v[12:13], v[12:13], v[40:41], v[20:21]
	v_pk_fma_f32 v[14:15], v[14:15], v[62:63], v[22:23]
	v_lshlrev_b32_e32 v55, 16, v37
	v_lshlrev_b32_e32 v54, 16, v36
	v_and_b32_e32 v37, 0xffff0000, v37
	v_and_b32_e32 v36, 0xffff0000, v36
	v_lshlrev_b32_e32 v61, 16, v39
	v_lshlrev_b32_e32 v60, 16, v38
	v_and_b32_e32 v39, 0xffff0000, v39
	v_and_b32_e32 v38, 0xffff0000, v38
	v_pk_fma_f32 v[16:17], v[16:17], v[52:53], v[24:25]
	v_pk_fma_f32 v[18:19], v[18:19], v[32:33], v[26:27]
	v_pk_fma_f32 v[4:5], v[4:5], v[58:59], v[12:13]
	v_pk_fma_f32 v[6:7], v[6:7], v[34:35], v[14:15]
	v_pk_fma_f32 v[8:9], v[8:9], v[54:55], v[16:17]
	v_pk_fma_f32 v[10:11], v[10:11], v[36:37], v[18:19]
	v_pk_fma_f32 v[0:1], v[0:1], v[60:61], v[4:5]
	v_pk_fma_f32 v[2:3], v[2:3], v[38:39], v[6:7]
	v_lshl_add_u64 v[42:43], s[24:25], 0, v[48:49]
	s_mov_b64 s[6:7], 0
	s_waitcnt vmcnt(0)
	v_lshlrev_b32_e32 v5, 16, v45
	v_lshlrev_b32_e32 v4, 16, v44
	v_and_b32_e32 v7, 0xffff0000, v45
	v_and_b32_e32 v6, 0xffff0000, v44
	v_lshlrev_b32_e32 v13, 16, v47
	v_lshlrev_b32_e32 v12, 16, v46
	v_and_b32_e32 v15, 0xffff0000, v47
	v_and_b32_e32 v14, 0xffff0000, v46
	v_pk_mul_f32 v[4:5], v[8:9], v[4:5]
	v_pk_mul_f32 v[6:7], v[10:11], v[6:7]
	v_pk_mul_f32 v[0:1], v[0:1], v[12:13]
	v_pk_mul_f32 v[2:3], v[2:3], v[14:15]
	v_and_b32_sdwa v10, v7, v143 dst_sel:DWORD dst_unused:UNUSED_PAD src0_sel:WORD_1 src1_sel:DWORD
	v_and_b32_sdwa v11, v6, v143 dst_sel:DWORD dst_unused:UNUSED_PAD src0_sel:WORD_1 src1_sel:DWORD
	v_and_b32_sdwa v12, v1, v143 dst_sel:DWORD dst_unused:UNUSED_PAD src0_sel:WORD_1 src1_sel:DWORD
	v_and_b32_sdwa v13, v0, v143 dst_sel:DWORD dst_unused:UNUSED_PAD src0_sel:WORD_1 src1_sel:DWORD
	v_and_b32_sdwa v14, v3, v143 dst_sel:DWORD dst_unused:UNUSED_PAD src0_sel:WORD_1 src1_sel:DWORD
	v_and_b32_sdwa v15, v2, v143 dst_sel:DWORD dst_unused:UNUSED_PAD src0_sel:WORD_1 src1_sel:DWORD
	v_cvt_pk_bf16_f32 v4, v4, v4
	v_cvt_pk_bf16_f32 v5, v5, v5
	v_cvt_pk_bf16_f32 v7, v7, v7
	v_cvt_pk_bf16_f32 v6, v6, v6
	v_cvt_pk_bf16_f32 v8, v0, v0
	v_cvt_pk_bf16_f32 v9, v1, v1
	v_cvt_pk_bf16_f32 v0, v3, v3
	v_cvt_pk_bf16_f32 v1, v2, v2
	v_and_b32_e32 v2, 0xffff0000, v7
	v_and_b32_e32 v3, 0xffff0000, v6
	v_and_b32_e32 v6, 0xffff0000, v0
	v_and_b32_e32 v7, 0xffff0000, v1
	v_or_b32_sdwa v1, v2, v5 dst_sel:DWORD dst_unused:UNUSED_PAD src0_sel:DWORD src1_sel:WORD_1
	v_or_b32_sdwa v0, v3, v4 dst_sel:DWORD dst_unused:UNUSED_PAD src0_sel:DWORD src1_sel:WORD_1
	v_or_b32_sdwa v3, v6, v9 dst_sel:DWORD dst_unused:UNUSED_PAD src0_sel:DWORD src1_sel:WORD_1
	v_or_b32_sdwa v2, v7, v8 dst_sel:DWORD dst_unused:UNUSED_PAD src0_sel:DWORD src1_sel:WORD_1
	global_store_dwordx4 v[42:43], v[0:3], off

.LBB0_199:
	v_cndmask_b32_e64 v134, v134, 0, s[26:27]
	v_cndmask_b32_e64 v101, v135, 0, s[26:27]
	v_add_f32_e32 v70, v134, v70
	v_add_f32_e32 v71, v101, v71
	v_cndmask_b32_e64 v70, v134, v70, s[6:7]
	v_cndmask_b32_e64 v71, v101, v71, s[6:7]
	v_add_f32_e32 v64, v70, v64
	v_add_f32_e32 v65, v71, v65
	v_cndmask_b32_e64 v64, v70, v64, s[8:9]
	v_cndmask_b32_e64 v65, v71, v65, s[8:9]
	v_add_f32_e32 v66, v64, v66
	v_add_f32_e32 v67, v65, v67
	v_cndmask_b32_e64 v200, v64, v66, s[10:11]
	v_cndmask_b32_e64 v101, v65, v67, s[10:11]
	v_add_f32_e32 v66, v132, v200
	v_add_f32_e32 v67, v133, v101
	v_mul_f32_e32 v66, 0x3fb8aa3b, v66
	v_exp_f32_e32 v70, v66
	v_mul_f32_e32 v66, 0x3fb8aa3b, v67
	v_exp_f32_e32 v71, v66
	v_add_f32_e32 v126, v126, v200
	v_mul_f32_e32 v126, 0x3fb8aa3b, v126
	v_exp_f32_e32 v126, v126
	v_rcp_f32_e32 v132, v71
	v_add_f32_e32 v71, v130, v200
	v_mul_f32_e32 v71, 0x3fb8aa3b, v71
	v_exp_f32_e32 v71, v71
	v_add_f32_e32 v133, v131, v101
	v_rcp_f32_e32 v70, v70
	v_mul_f32_e32 v133, 0x3fb8aa3b, v133
	v_rcp_f32_e32 v196, v71
	v_add_f32_e32 v71, v128, v200
	v_mul_f32_e32 v71, 0x3fb8aa3b, v71
	v_exp_f32_e32 v71, v71
	v_add_f32_e32 v128, v129, v101
	v_mul_f32_e32 v128, 0x3fb8aa3b, v128
	v_add_f32_e32 v127, v127, v101
	v_rcp_f32_e32 v71, v71
	v_exp_f32_e32 v133, v133
	v_exp_f32_e32 v128, v128
	v_mul_f32_e32 v127, 0x3fb8aa3b, v127
	v_rcp_f32_e32 v197, v126
	v_exp_f32_e32 v127, v127
	v_lshlrev_b32_e32 v65, 16, v193
	v_lshlrev_b32_e32 v64, 16, v189
	v_lshlrev_b32_e32 v131, 16, v194
	v_lshlrev_b32_e32 v130, 16, v190
	v_pk_mul_f32 v[64:65], v[70:71], v[64:65]
	v_rcp_f32_e32 v198, v133
	v_rcp_f32_e32 v133, v128
	v_pk_mul_f32 v[64:65], v[100:101], v[64:65] op_sel_hi:[0,1]
	v_pk_mul_f32 v[70:71], v[196:197], v[130:131]
	v_rcp_f32_e32 v199, v127
	v_pk_mul_f32 v[70:71], v[100:101], v[70:71] op_sel_hi:[0,1]
	v_cvt_pk_bf16_f32 v64, v64, v64
	v_cvt_pk_bf16_f32 v65, v65, v65
	v_and_b32_e32 v67, 0xffff0000, v193
	v_and_b32_e32 v66, 0xffff0000, v189
	v_cvt_pk_bf16_f32 v71, v71, v71
	v_cvt_pk_bf16_f32 v70, v70, v70
	v_and_b32_e32 v135, 0xffff0000, v194
	v_and_b32_e32 v134, 0xffff0000, v190
	v_and_b32_e32 v71, 0xffff0000, v71
	v_and_b32_e32 v70, 0xffff0000, v70
	v_pk_mul_f32 v[66:67], v[132:133], v[66:67]
	v_or_b32_sdwa v65, v71, v65 dst_sel:DWORD dst_unused:UNUSED_PAD src0_sel:DWORD src1_sel:WORD_1
	v_or_b32_sdwa v64, v70, v64 dst_sel:DWORD dst_unused:UNUSED_PAD src0_sel:DWORD src1_sel:WORD_1
	v_pk_mul_f32 v[66:67], v[74:75], v[66:67] op_sel_hi:[0,1]
	v_pk_mul_f32 v[70:71], v[198:199], v[134:135]
	s_nop 0
	v_pk_mul_f32 v[70:71], v[74:75], v[70:71] op_sel_hi:[0,1]
	v_cvt_pk_bf16_f32 v66, v66, v66
	v_cvt_pk_bf16_f32 v67, v67, v67
	v_cvt_pk_bf16_f32 v70, v70, v70
	v_cvt_pk_bf16_f32 v71, v71, v71
	v_and_b32_e32 v70, 0xffff0000, v70
	v_and_b32_e32 v71, 0xffff0000, v71
	v_or_b32_sdwa v126, v70, v66 dst_sel:DWORD dst_unused:UNUSED_PAD src0_sel:DWORD src1_sel:WORD_1
	v_add_f32_e32 v70, v124, v200
	v_or_b32_sdwa v127, v71, v67 dst_sel:DWORD dst_unused:UNUSED_PAD src0_sel:DWORD src1_sel:WORD_1
	v_add_f32_e32 v71, v125, v101
	v_mul_f32_e32 v70, 0x3fb8aa3b, v70
	v_exp_f32_e32 v124, v70
	v_mul_f32_e32 v70, 0x3fb8aa3b, v71
	v_exp_f32_e32 v125, v70
	v_add_f32_e32 v120, v120, v200
	v_mul_f32_e32 v120, 0x3fb8aa3b, v120
	v_add_f32_e32 v118, v118, v200
	v_rcp_f32_e32 v128, v125
	v_add_f32_e32 v125, v122, v200
	v_mul_f32_e32 v125, 0x3fb8aa3b, v125
	v_exp_f32_e32 v125, v125
	v_exp_f32_e32 v120, v120
	v_mul_f32_e32 v118, 0x3fb8aa3b, v118
	v_exp_f32_e32 v118, v118
	v_add_f32_e32 v119, v119, v101
	v_rcp_f32_e32 v124, v124
	v_add_f32_e32 v129, v123, v101
	v_rcp_f32_e32 v132, v125
	v_add_f32_e32 v121, v121, v101
	v_mul_f32_e32 v119, 0x3fb8aa3b, v119
	v_rcp_f32_e32 v125, v120
	v_mul_f32_e32 v129, 0x3fb8aa3b, v129
	v_mul_f32_e32 v121, 0x3fb8aa3b, v121
	v_exp_f32_e32 v119, v119
	v_rcp_f32_e32 v133, v118
	v_exp_f32_e32 v129, v129
	v_exp_f32_e32 v121, v121
	v_lshlrev_b32_e32 v67, 16, v191
	v_lshlrev_b32_e32 v66, 16, v185
	v_lshlrev_b32_e32 v123, 16, v192
	v_lshlrev_b32_e32 v122, 16, v187
	v_pk_mul_f32 v[66:67], v[124:125], v[66:67]
	v_rcp_f32_e32 v135, v119
	v_pk_mul_f32 v[66:67], v[100:101], v[66:67] op_sel_hi:[0,1]
	v_pk_mul_f32 v[118:119], v[132:133], v[122:123]
	v_rcp_f32_e32 v134, v129
	v_rcp_f32_e32 v129, v121
	v_pk_mul_f32 v[118:119], v[100:101], v[118:119] op_sel_hi:[0,1]
	v_cvt_pk_bf16_f32 v66, v66, v66
	v_cvt_pk_bf16_f32 v67, v67, v67
	v_cvt_pk_bf16_f32 v119, v119, v119
	v_cvt_pk_bf16_f32 v118, v118, v118
	v_and_b32_e32 v119, 0xffff0000, v119
	v_and_b32_e32 v118, 0xffff0000, v118
	v_and_b32_e32 v71, 0xffff0000, v191
	v_and_b32_e32 v70, 0xffff0000, v185
	v_or_b32_sdwa v67, v119, v67 dst_sel:DWORD dst_unused:UNUSED_PAD src0_sel:DWORD src1_sel:WORD_1
	v_or_b32_sdwa v66, v118, v66 dst_sel:DWORD dst_unused:UNUSED_PAD src0_sel:DWORD src1_sel:WORD_1
	v_and_b32_e32 v131, 0xffff0000, v192
	v_and_b32_e32 v130, 0xffff0000, v187
	ds_write_b128 v91, v[64:67] offset:34816
	v_pk_mul_f32 v[64:65], v[128:129], v[70:71]
	v_pk_mul_f32 v[66:67], v[134:135], v[130:131]
	v_pk_mul_f32 v[64:65], v[74:75], v[64:65] op_sel_hi:[0,1]
	v_pk_mul_f32 v[66:67], v[74:75], v[66:67] op_sel_hi:[0,1]
	v_cvt_pk_bf16_f32 v64, v64, v64
	v_cvt_pk_bf16_f32 v65, v65, v65
	v_cvt_pk_bf16_f32 v66, v66, v66
	v_cvt_pk_bf16_f32 v67, v67, v67
	v_and_b32_e32 v66, 0xffff0000, v66
	v_and_b32_e32 v67, 0xffff0000, v67
	v_or_b32_sdwa v128, v66, v64 dst_sel:DWORD dst_unused:UNUSED_PAD src0_sel:DWORD src1_sel:WORD_1
	v_add_f32_e32 v66, v116, v200
	v_or_b32_sdwa v129, v67, v65 dst_sel:DWORD dst_unused:UNUSED_PAD src0_sel:DWORD src1_sel:WORD_1
	v_add_f32_e32 v67, v117, v101
	v_mul_f32_e32 v66, 0x3fb8aa3b, v66
	v_exp_f32_e32 v70, v66
	v_mul_f32_e32 v66, 0x3fb8aa3b, v67
	v_exp_f32_e32 v71, v66
	v_add_f32_e32 v110, v110, v200
	v_mul_f32_e32 v110, 0x3fb8aa3b, v110
	v_exp_f32_e32 v110, v110
	v_rcp_f32_e32 v116, v71
	v_add_f32_e32 v71, v114, v200
	v_mul_f32_e32 v71, 0x3fb8aa3b, v71
	v_exp_f32_e32 v71, v71
	v_add_f32_e32 v117, v115, v101
	v_rcp_f32_e32 v70, v70
	v_mul_f32_e32 v117, 0x3fb8aa3b, v117
	v_rcp_f32_e32 v120, v71
	v_add_f32_e32 v71, v112, v200
	v_mul_f32_e32 v71, 0x3fb8aa3b, v71
	v_exp_f32_e32 v71, v71
	v_add_f32_e32 v112, v113, v101
	v_mul_f32_e32 v112, 0x3fb8aa3b, v112
	v_add_f32_e32 v111, v111, v101
	v_rcp_f32_e32 v71, v71
	v_exp_f32_e32 v117, v117
	v_exp_f32_e32 v112, v112
	v_mul_f32_e32 v111, 0x3fb8aa3b, v111
	v_rcp_f32_e32 v121, v110
	v_exp_f32_e32 v111, v111
	v_lshlrev_b32_e32 v65, 16, v183
	v_lshlrev_b32_e32 v64, 16, v180
	s_waitcnt vmcnt(14)
	v_lshlrev_b32_e32 v115, 16, v195
	v_lshlrev_b32_e32 v114, 16, v181
	v_pk_mul_f32 v[64:65], v[70:71], v[64:65]
	v_rcp_f32_e32 v122, v117
	v_rcp_f32_e32 v117, v112
	v_pk_mul_f32 v[64:65], v[100:101], v[64:65] op_sel_hi:[0,1]
	v_pk_mul_f32 v[70:71], v[120:121], v[114:115]
	v_rcp_f32_e32 v123, v111
	v_pk_mul_f32 v[70:71], v[100:101], v[70:71] op_sel_hi:[0,1]
	v_cvt_pk_bf16_f32 v64, v64, v64
	v_cvt_pk_bf16_f32 v65, v65, v65
	v_and_b32_e32 v67, 0xffff0000, v183
	v_and_b32_e32 v66, 0xffff0000, v180
	v_cvt_pk_bf16_f32 v71, v71, v71
	v_cvt_pk_bf16_f32 v70, v70, v70
	v_and_b32_e32 v119, 0xffff0000, v195
	v_and_b32_e32 v118, 0xffff0000, v181
	v_and_b32_e32 v71, 0xffff0000, v71
	v_and_b32_e32 v70, 0xffff0000, v70
	v_pk_mul_f32 v[66:67], v[116:117], v[66:67]
	v_or_b32_sdwa v65, v71, v65 dst_sel:DWORD dst_unused:UNUSED_PAD src0_sel:DWORD src1_sel:WORD_1
	v_or_b32_sdwa v64, v70, v64 dst_sel:DWORD dst_unused:UNUSED_PAD src0_sel:DWORD src1_sel:WORD_1
	v_pk_mul_f32 v[66:67], v[74:75], v[66:67] op_sel_hi:[0,1]
	v_pk_mul_f32 v[70:71], v[122:123], v[118:119]
	s_nop 0
	v_pk_mul_f32 v[70:71], v[74:75], v[70:71] op_sel_hi:[0,1]
	v_cvt_pk_bf16_f32 v66, v66, v66
	v_cvt_pk_bf16_f32 v67, v67, v67
	v_cvt_pk_bf16_f32 v70, v70, v70
	v_cvt_pk_bf16_f32 v71, v71, v71
	v_and_b32_e32 v70, 0xffff0000, v70
	v_and_b32_e32 v71, 0xffff0000, v71
	v_or_b32_sdwa v110, v70, v66 dst_sel:DWORD dst_unused:UNUSED_PAD src0_sel:DWORD src1_sel:WORD_1
	v_add_f32_e32 v70, v108, v200
	v_or_b32_sdwa v111, v71, v67 dst_sel:DWORD dst_unused:UNUSED_PAD src0_sel:DWORD src1_sel:WORD_1
	v_add_f32_e32 v71, v109, v101
	v_mul_f32_e32 v70, 0x3fb8aa3b, v70
	v_exp_f32_e32 v108, v70
	v_mul_f32_e32 v70, 0x3fb8aa3b, v71
	v_exp_f32_e32 v109, v70
	v_add_f32_e32 v104, v104, v200
	v_mul_f32_e32 v104, 0x3fb8aa3b, v104
	v_add_f32_e32 v102, v102, v200
	v_rcp_f32_e32 v112, v109
	v_add_f32_e32 v109, v106, v200
	v_mul_f32_e32 v109, 0x3fb8aa3b, v109
	v_exp_f32_e32 v109, v109
	v_exp_f32_e32 v104, v104
	v_mul_f32_e32 v102, 0x3fb8aa3b, v102
	v_exp_f32_e32 v102, v102
	v_add_f32_e32 v113, v107, v101
	v_add_f32_e32 v105, v105, v101
	v_add_f32_e32 v101, v103, v101
	v_rcp_f32_e32 v108, v108
	v_rcp_f32_e32 v116, v109
	v_mul_f32_e32 v101, 0x3fb8aa3b, v101
	v_rcp_f32_e32 v109, v104
	v_exp_f32_e32 v101, v101
	v_rcp_f32_e32 v117, v102
	v_mul_f32_e32 v113, 0x3fb8aa3b, v113
	v_mul_f32_e32 v105, 0x3fb8aa3b, v105
	s_waitcnt vmcnt(5)
	v_lshlrev_b32_e32 v67, 16, v188
	v_lshlrev_b32_e32 v66, 16, v184
	v_exp_f32_e32 v113, v113
	v_exp_f32_e32 v105, v105
	s_waitcnt vmcnt(2)
	v_lshlrev_b32_e32 v107, 16, v186
	v_lshlrev_b32_e32 v106, 16, v182
	v_pk_mul_f32 v[66:67], v[108:109], v[66:67]
	v_pk_mul_f32 v[102:103], v[116:117], v[106:107]
	v_pk_mul_f32 v[66:67], v[100:101], v[66:67] op_sel_hi:[0,1]
	v_rcp_f32_e32 v119, v101
	v_pk_mul_f32 v[100:101], v[100:101], v[102:103] op_sel_hi:[0,1]
	v_rcp_f32_e32 v118, v113
	v_rcp_f32_e32 v113, v105
	v_cvt_pk_bf16_f32 v66, v66, v66
	v_cvt_pk_bf16_f32 v67, v67, v67
	v_cvt_pk_bf16_f32 v101, v101, v101
	v_cvt_pk_bf16_f32 v100, v100, v100
	v_and_b32_e32 v101, 0xffff0000, v101
	v_and_b32_e32 v100, 0xffff0000, v100
	v_and_b32_e32 v71, 0xffff0000, v188
	v_and_b32_e32 v70, 0xffff0000, v184
	v_or_b32_sdwa v67, v101, v67 dst_sel:DWORD dst_unused:UNUSED_PAD src0_sel:DWORD src1_sel:WORD_1
	v_or_b32_sdwa v66, v100, v66 dst_sel:DWORD dst_unused:UNUSED_PAD src0_sel:DWORD src1_sel:WORD_1
	v_and_b32_e32 v115, 0xffff0000, v186
	v_and_b32_e32 v114, 0xffff0000, v182
	ds_write_b128 v91, v[64:67] offset:34832
	v_pk_mul_f32 v[64:65], v[112:113], v[70:71]
	v_pk_mul_f32 v[66:67], v[118:119], v[114:115]
	v_pk_mul_f32 v[64:65], v[74:75], v[64:65] op_sel_hi:[0,1]
	v_pk_mul_f32 v[66:67], v[74:75], v[66:67] op_sel_hi:[0,1]
	v_cvt_pk_bf16_f32 v64, v64, v64
	v_cvt_pk_bf16_f32 v65, v65, v65
	v_cvt_pk_bf16_f32 v67, v67, v67
	v_cvt_pk_bf16_f32 v66, v66, v66
	v_lshlrev_b32_e32 v70, 16, v173
	v_and_b32_e32 v67, 0xffff0000, v67
	v_and_b32_e32 v66, 0xffff0000, v66
	v_or_b32_sdwa v100, v70, v172 dst_sel:DWORD dst_unused:UNUSED_PAD src0_sel:DWORD src1_sel:WORD_0
	v_lshlrev_b32_e32 v70, 16, v175
	v_or_b32_sdwa v113, v67, v65 dst_sel:DWORD dst_unused:UNUSED_PAD src0_sel:DWORD src1_sel:WORD_1
	v_or_b32_sdwa v112, v66, v64 dst_sel:DWORD dst_unused:UNUSED_PAD src0_sel:DWORD src1_sel:WORD_1
	v_lshlrev_b32_e32 v64, 16, v157
	v_lshlrev_b32_e32 v65, 16, v159
	v_lshlrev_b32_e32 v66, 16, v166
	v_lshlrev_b32_e32 v67, 16, v171
	v_or_b32_sdwa v101, v70, v174 dst_sel:DWORD dst_unused:UNUSED_PAD src0_sel:DWORD src1_sel:WORD_0
	v_lshlrev_b32_e32 v70, 16, v177
	v_or_b32_sdwa v64, v64, v156 dst_sel:DWORD dst_unused:UNUSED_PAD src0_sel:DWORD src1_sel:WORD_0
	v_or_b32_sdwa v65, v65, v158 dst_sel:DWORD dst_unused:UNUSED_PAD src0_sel:DWORD src1_sel:WORD_0
	v_or_b32_sdwa v66, v66, v160 dst_sel:DWORD dst_unused:UNUSED_PAD src0_sel:DWORD src1_sel:WORD_0
	v_or_b32_sdwa v67, v67, v170 dst_sel:DWORD dst_unused:UNUSED_PAD src0_sel:DWORD src1_sel:WORD_0
	v_or_b32_sdwa v102, v70, v176 dst_sel:DWORD dst_unused:UNUSED_PAD src0_sel:DWORD src1_sel:WORD_0
	s_waitcnt vmcnt(1)
	v_lshlrev_b32_e32 v70, 16, v179
	v_add_u32_e32 v166, s43, v140
	ds_write_b128 v91, v[126:129] offset:34960
	ds_write_b128 v91, v[110:113] offset:34976
	s_waitcnt lgkmcnt(0)
	s_barrier
	v_or_b32_sdwa v103, v70, v178 dst_sel:DWORD dst_unused:UNUSED_PAD src0_sel:DWORD src1_sel:WORD_0
	ds_write_b128 v144, v[64:67] offset:53248
	ds_write_b128 v144, v[100:103] offset:53264
	s_waitcnt lgkmcnt(0)
	s_barrier
	ds_read_b128 v[64:67], v166 offset:53248
	ds_read2_b32 v[70:71], v145 offset1:16
	ds_read2_b32 v[170:171], v145 offset0:32 offset1:48
	v_add_u32_e32 v172, s44, v140
	ds_read_b128 v[100:103], v172 offset:34816
	ds_read_b128 v[104:107], v172 offset:37120
	ds_read_b128 v[108:111], v166 offset:53312
	ds_read_b128 v[112:115], v172 offset:34880
	ds_read_b128 v[116:119], v172 offset:39424
	ds_read_b128 v[120:123], v172 offset:37184
	ds_read_b128 v[124:127], v166 offset:55552
	ds_read_b128 v[128:131], v172 offset:41728
	ds_read_b128 v[132:135], v172 offset:39488
	s_waitcnt lgkmcnt(10)
	v_mov_b32_e32 v74, v71
	s_waitcnt lgkmcnt(9)
	v_mov_b32_e32 v160, v171
	v_pk_mul_f32 v[62:63], v[62:63], v[70:71] op_sel_hi:[1,0]
	v_pk_mul_f32 v[60:61], v[60:61], v[70:71] op_sel_hi:[1,0]
	v_pk_mul_f32 v[58:59], v[58:59], v[74:75] op_sel_hi:[1,0]
	v_pk_mul_f32 v[56:57], v[56:57], v[74:75] op_sel_hi:[1,0]
	v_pk_mul_f32 v[54:55], v[54:55], v[170:171] op_sel_hi:[1,0]
	v_pk_mul_f32 v[52:53], v[52:53], v[170:171] op_sel_hi:[1,0]
	v_pk_mul_f32 v[46:47], v[46:47], v[160:161] op_sel_hi:[1,0]
	v_pk_mul_f32 v[44:45], v[44:45], v[160:161] op_sel_hi:[1,0]
	s_waitcnt lgkmcnt(8)
	v_mfma_f32_16x16x32_bf16 v[60:63], v[64:67], v[100:103], v[60:63]
	ds_read_b128 v[156:159], v172 offset:41792
	v_pk_mul_f32 v[42:43], v[42:43], v[70:71] op_sel_hi:[1,0]
	v_pk_mul_f32 v[40:41], v[40:41], v[70:71] op_sel_hi:[1,0]
	s_waitcnt lgkmcnt(8)
	v_mfma_f32_16x16x32_bf16 v[56:59], v[64:67], v[104:107], v[56:59]
	v_lshlrev_b32_e32 v70, 16, v147
	v_pk_mul_f32 v[38:39], v[38:39], v[74:75] op_sel_hi:[1,0]
	v_pk_mul_f32 v[36:37], v[36:37], v[74:75] op_sel_hi:[1,0]
	s_waitcnt lgkmcnt(5)
	v_mfma_f32_16x16x32_bf16 v[52:55], v[64:67], v[116:119], v[52:55]
	v_mul_f32_e64 v30, v30, v170
	v_mul_f32_e64 v31, v31, v170
	v_pk_mul_f32 v[28:29], v[28:29], v[170:171] op_sel_hi:[1,0]
	v_pk_mul_f32 v[34:35], v[34:35], v[160:161] op_sel_hi:[1,0]
	s_waitcnt lgkmcnt(2)
	v_mfma_f32_16x16x32_bf16 v[44:47], v[64:67], v[128:131], v[44:47]
	ds_read_b128 v[64:67], v166 offset:55616
	v_pk_mul_f32 v[32:33], v[32:33], v[160:161] op_sel_hi:[1,0]
	s_waitcnt lgkmcnt(0)
	v_mfma_f32_16x16x32_bf16 v[40:43], v[124:127], v[100:103], v[40:43]
	v_or_b32_sdwa v100, v70, v146 dst_sel:DWORD dst_unused:UNUSED_PAD src0_sel:DWORD src1_sel:WORD_0
	v_lshlrev_b32_e32 v70, 16, v149
	v_or_b32_sdwa v101, v70, v148 dst_sel:DWORD dst_unused:UNUSED_PAD src0_sel:DWORD src1_sel:WORD_0
	v_lshlrev_b32_e32 v70, 16, v151
	v_or_b32_sdwa v102, v70, v150 dst_sel:DWORD dst_unused:UNUSED_PAD src0_sel:DWORD src1_sel:WORD_0
	v_lshlrev_b32_e32 v70, 16, v153
	v_mfma_f32_16x16x32_bf16 v[36:39], v[124:127], v[104:107], v[36:39]
	v_or_b32_sdwa v103, v70, v152 dst_sel:DWORD dst_unused:UNUSED_PAD src0_sel:DWORD src1_sel:WORD_0
	v_lshlrev_b32_e32 v70, 16, v155
	v_or_b32_sdwa v104, v70, v154 dst_sel:DWORD dst_unused:UNUSED_PAD src0_sel:DWORD src1_sel:WORD_0
	v_mfma_f32_16x16x32_bf16 v[28:31], v[124:127], v[116:119], v[28:31]
	v_lshlrev_b32_e32 v70, 16, v162
	v_or_b32_sdwa v105, v70, v161 dst_sel:DWORD dst_unused:UNUSED_PAD src0_sel:DWORD src1_sel:WORD_0
	v_lshlrev_b32_e32 v70, 16, v164
	v_mfma_f32_16x16x32_bf16 v[32:35], v[124:127], v[128:131], v[32:35]
	v_or_b32_sdwa v106, v70, v163 dst_sel:DWORD dst_unused:UNUSED_PAD src0_sel:DWORD src1_sel:WORD_0
	s_waitcnt vmcnt(0)
	v_lshlrev_b32_e32 v70, 16, v167
	s_barrier
	v_mfma_f32_16x16x32_bf16 v[40:43], v[64:67], v[112:115], v[40:43]
	v_or_b32_sdwa v107, v70, v165 dst_sel:DWORD dst_unused:UNUSED_PAD src0_sel:DWORD src1_sel:WORD_0
	ds_write_b128 v144, v[100:103] offset:53248
	ds_write_b128 v144, v[104:107] offset:53264
	v_mfma_f32_16x16x32_bf16 v[36:39], v[64:67], v[120:123], v[36:39]
	s_waitcnt lgkmcnt(0)
	s_barrier
	v_mfma_f32_16x16x32_bf16 v[28:31], v[64:67], v[132:135], v[28:31]
	ds_read2_b32 v[70:71], v145 offset1:16
	ds_read2_b32 v[150:151], v145 offset0:32 offset1:48
	ds_read_b128 v[100:103], v172 offset:34816
	v_mfma_f32_16x16x32_bf16 v[32:35], v[64:67], v[156:159], v[32:35]
	ds_read_b128 v[64:67], v166 offset:53248
	s_waitcnt lgkmcnt(3)
	v_mov_b32_e32 v74, v71
	s_waitcnt lgkmcnt(2)
	v_mov_b32_e32 v152, v151
	v_mfma_f32_16x16x32_bf16 v[60:63], v[108:111], v[112:115], v[60:63]
	v_mul_f32_e64 v50, v50, v70
	v_mul_f32_e64 v51, v51, v70
	v_pk_mul_f32 v[48:49], v[48:49], v[70:71] op_sel_hi:[1,0]
	v_pk_mul_f32 v[26:27], v[26:27], v[74:75] op_sel_hi:[1,0]
	v_mfma_f32_16x16x32_bf16 v[56:59], v[108:111], v[120:123], v[56:59]
	v_mul_f32_e64 v24, v24, v74
	v_mul_f32_e64 v25, v25, v74
	v_pk_mul_f32 v[22:23], v[22:23], v[150:151] op_sel_hi:[1,0]
	v_pk_mul_f32 v[20:21], v[20:21], v[150:151] op_sel_hi:[1,0]
	v_mfma_f32_16x16x32_bf16 v[52:55], v[108:111], v[132:135], v[52:55]
	v_mul_f32_e64 v14, v14, v152
	v_mul_f32_e64 v15, v15, v152
	v_pk_mul_f32 v[12:13], v[12:13], v[152:153] op_sel_hi:[1,0]
	v_pk_mul_f32 v[10:11], v[10:11], v[70:71] op_sel_hi:[1,0]
	v_mfma_f32_16x16x32_bf16 v[44:47], v[108:111], v[156:159], v[44:47]
	ds_read_b128 v[104:107], v172 offset:37120
	ds_read_b128 v[108:111], v166 offset:53312
	ds_read_b128 v[112:115], v172 offset:34880
	ds_read_b128 v[116:119], v172 offset:39424
	ds_read_b128 v[120:123], v172 offset:37184
	ds_read_b128 v[124:127], v166 offset:55552
	ds_read_b128 v[128:131], v172 offset:41728
	ds_read_b128 v[132:135], v172 offset:39488
	s_waitcnt lgkmcnt(8)
	v_mfma_f32_16x16x32_bf16 v[48:51], v[64:67], v[100:103], v[48:51]
	ds_read_b128 v[146:149], v172 offset:41792
	v_pk_mul_f32 v[8:9], v[8:9], v[70:71] op_sel_hi:[1,0]
	v_pk_mul_f32 v[6:7], v[6:7], v[74:75] op_sel_hi:[1,0]
	s_waitcnt lgkmcnt(8)
	v_mfma_f32_16x16x32_bf16 v[24:27], v[64:67], v[104:107], v[24:27]
	v_mul_f32_e64 v4, v4, v74
	v_mul_f32_e64 v5, v5, v74
	v_pk_mul_f32 v[2:3], v[2:3], v[150:151] op_sel_hi:[1,0]
	v_pk_mul_f32 v[0:1], v[0:1], v[150:151] op_sel_hi:[1,0]
	s_waitcnt lgkmcnt(5)
	v_mfma_f32_16x16x32_bf16 v[20:23], v[64:67], v[116:119], v[20:23]
	v_mul_f32_e64 v18, v18, v152
	v_mul_f32_e64 v19, v19, v152
	v_pk_mul_f32 v[16:17], v[16:17], v[152:153] op_sel_hi:[1,0]
	s_add_i32 s40, s40, 64
	s_waitcnt lgkmcnt(2)
	v_mfma_f32_16x16x32_bf16 v[12:15], v[64:67], v[128:131], v[12:15]
	ds_read_b128 v[64:67], v166 offset:55616
	s_sub_i32 s45, s45, 64
	v_pk_add_f32 v[92:93], v[92:93], v[68:69]
	v_mfma_f32_16x16x32_bf16 v[8:11], v[124:127], v[100:103], v[8:11]
	s_cmpk_eq_i32 s40, 0x200
	v_mfma_f32_16x16x32_bf16 v[4:7], v[124:127], v[104:107], v[4:7]
	v_mfma_f32_16x16x32_bf16 v[0:3], v[124:127], v[116:119], v[0:3]
	v_mfma_f32_16x16x32_bf16 v[16:19], v[124:127], v[128:131], v[16:19]
	v_mfma_f32_16x16x32_bf16 v[48:51], v[108:111], v[112:115], v[48:51]
	v_mfma_f32_16x16x32_bf16 v[24:27], v[108:111], v[120:123], v[24:27]
	s_waitcnt lgkmcnt(2)
	v_mfma_f32_16x16x32_bf16 v[20:23], v[108:111], v[132:135], v[20:23]
	s_waitcnt lgkmcnt(1)
	v_mfma_f32_16x16x32_bf16 v[12:15], v[108:111], v[146:149], v[12:15]
	s_waitcnt lgkmcnt(0)
	v_mfma_f32_16x16x32_bf16 v[8:11], v[64:67], v[112:115], v[8:11]
	v_mfma_f32_16x16x32_bf16 v[4:7], v[64:67], v[120:123], v[4:7]
	v_mfma_f32_16x16x32_bf16 v[0:3], v[64:67], v[132:135], v[0:3]
	v_mfma_f32_16x16x32_bf16 v[16:19], v[64:67], v[146:149], v[16:19]
	s_cbranch_scc1 .LBB0_202

.LBB0_334:
	v_cndmask_b32_e64 v216, v216, 0, s[58:59]
	v_cndmask_b32_e64 v215, v215, 0, s[58:59]
	v_add_f32_e32 v70, v215, v70
	v_add_f32_e32 v71, v216, v71
	v_cndmask_b32_e64 v71, v216, v71, s[8:9]
	v_cndmask_b32_e64 v70, v215, v70, s[8:9]
	v_add_f32_e32 v64, v70, v64
	v_add_f32_e32 v65, v71, v65
	v_cndmask_b32_e64 v65, v71, v65, s[10:11]
	v_cndmask_b32_e64 v70, v70, v64, s[10:11]
	v_add_f32_e32 v66, v70, v66
	v_add_f32_e32 v64, v65, v67
	v_cndmask_b32_e64 v64, v65, v64, s[12:13]
	v_cndmask_b32_e64 v65, v70, v66, s[12:13]
	v_add_f32_e32 v66, v122, v65
	v_mul_f32_e32 v66, 0x3fb8aa3b, v66
	v_exp_f32_e32 v66, v66
	v_add_f32_e32 v67, v123, v64
	v_mul_f32_e32 v67, 0x3fb8aa3b, v67
	v_exp_f32_e32 v67, v67
	v_rcp_f32_e32 v70, v66
	v_add_f32_e32 v121, v121, v64
	v_mul_f32_e32 v121, 0x3fb8aa3b, v121
	v_rcp_f32_e32 v71, v67
	v_lshlrev_b32_e32 v122, 16, v214
	v_exp_f32_e32 v121, v121
	v_mul_f32_e32 v70, v70, v122
	v_lshlrev_b32_e32 v122, 16, v213
	v_mul_f32_e32 v66, v66, v122
	v_and_b32_e32 v122, 0xffff0000, v213
	v_and_b32_e32 v123, 0xffff0000, v214
	v_mul_f32_e32 v67, v67, v122
	v_add_f32_e32 v120, v120, v65
	v_mul_f32_e32 v71, v71, v123
	v_cvt_pk_bf16_f32 v66, v66, v66
	v_mul_f32_e32 v120, 0x3fb8aa3b, v120
	v_rcp_f32_e32 v123, v121
	v_lshrrev_b32_e32 v66, 16, v66
	v_cvt_pk_bf16_f32 v67, v67, v67
	v_exp_f32_e32 v120, v120
	v_and_or_b32 v66, v67, s63, v66
	v_cvt_pk_bf16_f32 v67, v70, v70
	v_lshlrev_b32_e32 v213, 16, v212
	v_and_b32_e32 v212, 0xffff0000, v212
	v_lshrrev_b32_e32 v67, 16, v67
	v_cvt_pk_bf16_f32 v122, v71, v71
	v_mul_f32_e32 v123, v123, v212
	v_lshlrev_b32_e32 v212, 16, v211
	v_and_or_b32 v67, v122, s63, v67
	v_rcp_f32_e32 v122, v120
	v_mul_f32_e32 v120, v120, v212
	v_and_b32_e32 v211, 0xffff0000, v211
	v_mul_f32_e32 v121, v121, v211
	v_cvt_pk_bf16_f32 v120, v120, v120
	v_lshrrev_b32_e32 v120, 16, v120
	v_cvt_pk_bf16_f32 v121, v121, v121
	v_mul_f32_e32 v122, v122, v213
	v_and_or_b32 v120, v121, s63, v120
	ds_write2_b32 v137, v66, v120 offset1:68
	v_cvt_pk_bf16_f32 v66, v122, v122
	v_lshrrev_b32_e32 v66, 16, v66
	v_cvt_pk_bf16_f32 v120, v123, v123
	v_mul_f32_e32 v70, v68, v70
	v_and_or_b32 v66, v120, s63, v66
	v_add_u32_e32 v120, 0x4400, v137
	ds_write2_b32 v120, v67, v66 offset1:68
	v_mul_f32_e32 v66, v68, v122
	v_cvt_pk_bf16_f32 v70, v70, v70
	v_mul_f32_e32 v67, v69, v123
	v_lshrrev_b32_e32 v70, 16, v70
	v_cvt_pk_bf16_f32 v66, v66, v66
	v_and_or_b32 v66, v66, s63, v70
	v_cvt_pk_bf16_f32 v67, v67, v67
	v_add_f32_e32 v70, v118, v65
	v_mul_f32_e32 v71, v69, v71
	v_mul_f32_e32 v70, 0x3fb8aa3b, v70
	ds_write_b32 v74, v66 offset:34816
	v_exp_f32_e32 v70, v70
	v_cvt_pk_bf16_f32 v66, v71, v71
	v_lshrrev_b32_e32 v66, 16, v66
	v_add_f32_e32 v71, v119, v64
	v_and_or_b32 v66, v67, s63, v66
	v_mul_f32_e32 v71, 0x3fb8aa3b, v71
	ds_write_b32 v74, v66 offset:34960
	v_rcp_f32_e32 v66, v70
	v_exp_f32_e32 v71, v71
	v_lshlrev_b32_e32 v118, 16, v210
	v_add_f32_e32 v116, v116, v65
	v_mul_f32_e32 v66, v66, v118
	v_lshlrev_b32_e32 v118, 16, v209
	v_rcp_f32_e32 v67, v71
	v_mul_f32_e32 v70, v70, v118
	v_and_b32_e32 v118, 0xffff0000, v209
	v_mul_f32_e32 v71, v71, v118
	v_cvt_pk_bf16_f32 v70, v70, v70
	v_mul_f32_e32 v116, 0x3fb8aa3b, v116
	v_and_b32_e32 v119, 0xffff0000, v210
	v_lshrrev_b32_e32 v70, 16, v70
	v_cvt_pk_bf16_f32 v71, v71, v71
	v_exp_f32_e32 v116, v116
	v_mul_f32_e32 v67, v67, v119
	v_and_or_b32 v70, v71, s63, v70
	v_cvt_pk_bf16_f32 v71, v66, v66
	v_lshrrev_b32_e32 v71, 16, v71
	v_cvt_pk_bf16_f32 v118, v67, v67
	v_and_or_b32 v71, v118, s63, v71
	v_add_f32_e32 v117, v117, v64
	v_rcp_f32_e32 v118, v116
	v_mul_f32_e32 v117, 0x3fb8aa3b, v117
	v_exp_f32_e32 v117, v117
	v_lshlrev_b32_e32 v121, 16, v208
	v_mul_f32_e32 v118, v118, v121
	v_lshlrev_b32_e32 v121, 16, v207
	v_mul_f32_e32 v116, v116, v121
	v_and_b32_e32 v121, 0xffff0000, v207
	v_rcp_f32_e32 v119, v117
	v_mul_f32_e32 v117, v117, v121
	v_cvt_pk_bf16_f32 v116, v116, v116
	v_lshrrev_b32_e32 v116, 16, v116
	v_cvt_pk_bf16_f32 v117, v117, v117
	v_and_b32_e32 v122, 0xffff0000, v208
	v_and_or_b32 v116, v117, s63, v116
	v_mul_f32_e32 v119, v119, v122
	ds_write2_b32 v137, v70, v116 offset0:136 offset1:204
	v_cvt_pk_bf16_f32 v70, v118, v118
	v_lshrrev_b32_e32 v70, 16, v70
	v_cvt_pk_bf16_f32 v116, v119, v119
	v_mul_f32_e32 v66, v68, v66
	v_and_or_b32 v70, v116, s63, v70
	ds_write2_b32 v120, v71, v70 offset0:136 offset1:204
	v_mul_f32_e32 v70, v68, v118
	v_cvt_pk_bf16_f32 v66, v66, v66
	v_lshrrev_b32_e32 v66, 16, v66
	v_cvt_pk_bf16_f32 v70, v70, v70
	v_and_or_b32 v66, v70, s63, v66
	v_add_f32_e32 v70, v114, v65
	v_mul_f32_e32 v67, v69, v67
	v_mul_f32_e32 v70, 0x3fb8aa3b, v70
	v_mul_f32_e32 v71, v69, v119
	ds_write_b32 v74, v66 offset:34820
	v_exp_f32_e32 v70, v70
	v_cvt_pk_bf16_f32 v66, v67, v67
	v_lshrrev_b32_e32 v66, 16, v66
	v_cvt_pk_bf16_f32 v67, v71, v71
	v_add_f32_e32 v71, v115, v64
	v_and_or_b32 v66, v67, s63, v66
	v_mul_f32_e32 v71, 0x3fb8aa3b, v71
	ds_write_b32 v74, v66 offset:34964
	v_rcp_f32_e32 v66, v70
	v_exp_f32_e32 v71, v71
	v_lshlrev_b32_e32 v114, 16, v206
	v_add_f32_e32 v112, v112, v65
	v_mul_f32_e32 v66, v66, v114
	v_lshlrev_b32_e32 v114, 16, v205
	v_rcp_f32_e32 v67, v71
	v_mul_f32_e32 v70, v70, v114
	v_and_b32_e32 v114, 0xffff0000, v205
	v_mul_f32_e32 v71, v71, v114
	v_cvt_pk_bf16_f32 v70, v70, v70
	v_mul_f32_e32 v112, 0x3fb8aa3b, v112
	v_and_b32_e32 v115, 0xffff0000, v206
	v_lshrrev_b32_e32 v70, 16, v70
	v_cvt_pk_bf16_f32 v71, v71, v71
	v_exp_f32_e32 v112, v112
	v_mul_f32_e32 v67, v67, v115
	v_and_or_b32 v70, v71, s63, v70
	v_cvt_pk_bf16_f32 v71, v66, v66
	v_lshrrev_b32_e32 v71, 16, v71
	v_cvt_pk_bf16_f32 v114, v67, v67
	v_and_or_b32 v71, v114, s63, v71
	v_add_f32_e32 v113, v113, v64
	v_rcp_f32_e32 v114, v112
	v_mul_f32_e32 v113, 0x3fb8aa3b, v113
	v_exp_f32_e32 v113, v113
	v_lshlrev_b32_e32 v116, 16, v204
	v_mul_f32_e32 v114, v114, v116
	v_lshlrev_b32_e32 v116, 16, v203
	v_mul_f32_e32 v112, v112, v116
	v_and_b32_e32 v116, 0xffff0000, v203
	v_rcp_f32_e32 v115, v113
	v_mul_f32_e32 v113, v113, v116
	v_cvt_pk_bf16_f32 v112, v112, v112
	v_lshrrev_b32_e32 v112, 16, v112
	v_cvt_pk_bf16_f32 v113, v113, v113
	v_and_b32_e32 v117, 0xffff0000, v204
	v_and_or_b32 v112, v113, s63, v112
	v_add_u32_e32 v113, 0x400, v137
	v_mul_f32_e32 v115, v115, v117
	ds_write2_b32 v113, v70, v112 offset0:16 offset1:84
	v_cvt_pk_bf16_f32 v70, v114, v114
	v_lshrrev_b32_e32 v70, 16, v70
	v_cvt_pk_bf16_f32 v112, v115, v115
	v_mul_f32_e32 v66, v68, v66
	v_and_or_b32 v70, v112, s63, v70
	v_add_u32_e32 v112, 0x4800, v137
	ds_write2_b32 v112, v71, v70 offset0:16 offset1:84
	v_mul_f32_e32 v70, v68, v114
	v_cvt_pk_bf16_f32 v66, v66, v66
	v_lshrrev_b32_e32 v66, 16, v66
	v_cvt_pk_bf16_f32 v70, v70, v70
	v_and_or_b32 v66, v70, s63, v66
	v_add_f32_e32 v70, v110, v65
	v_mul_f32_e32 v67, v69, v67
	v_mul_f32_e32 v70, 0x3fb8aa3b, v70
	v_mul_f32_e32 v71, v69, v115
	ds_write_b32 v74, v66 offset:34824
	v_exp_f32_e32 v70, v70
	v_cvt_pk_bf16_f32 v66, v67, v67
	v_lshrrev_b32_e32 v66, 16, v66
	v_cvt_pk_bf16_f32 v67, v71, v71
	v_add_f32_e32 v71, v111, v64
	v_and_or_b32 v66, v67, s63, v66
	v_mul_f32_e32 v71, 0x3fb8aa3b, v71
	ds_write_b32 v74, v66 offset:34968
	v_rcp_f32_e32 v66, v70
	v_exp_f32_e32 v71, v71
	v_lshlrev_b32_e32 v110, 16, v202
	v_add_f32_e32 v108, v108, v65
	v_mul_f32_e32 v66, v66, v110
	v_lshlrev_b32_e32 v110, 16, v201
	v_rcp_f32_e32 v67, v71
	v_mul_f32_e32 v70, v70, v110
	v_and_b32_e32 v110, 0xffff0000, v201
	v_mul_f32_e32 v71, v71, v110
	v_cvt_pk_bf16_f32 v70, v70, v70
	v_mul_f32_e32 v108, 0x3fb8aa3b, v108
	v_and_b32_e32 v111, 0xffff0000, v202
	v_lshrrev_b32_e32 v70, 16, v70
	v_cvt_pk_bf16_f32 v71, v71, v71
	v_exp_f32_e32 v108, v108
	v_mul_f32_e32 v67, v67, v111
	v_and_or_b32 v70, v71, s63, v70
	v_cvt_pk_bf16_f32 v71, v66, v66
	v_lshrrev_b32_e32 v71, 16, v71
	v_cvt_pk_bf16_f32 v110, v67, v67
	v_and_or_b32 v71, v110, s63, v71
	v_add_f32_e32 v109, v109, v64
	v_rcp_f32_e32 v110, v108
	v_mul_f32_e32 v109, 0x3fb8aa3b, v109
	v_exp_f32_e32 v109, v109
	v_lshlrev_b32_e32 v114, 16, v200
	v_mul_f32_e32 v110, v110, v114
	v_lshlrev_b32_e32 v114, 16, v199
	v_mul_f32_e32 v108, v108, v114
	v_and_b32_e32 v114, 0xffff0000, v199
	v_rcp_f32_e32 v111, v109
	v_mul_f32_e32 v109, v109, v114
	v_cvt_pk_bf16_f32 v108, v108, v108
	v_lshrrev_b32_e32 v108, 16, v108
	v_cvt_pk_bf16_f32 v109, v109, v109
	v_and_b32_e32 v115, 0xffff0000, v200
	v_and_or_b32 v108, v109, s63, v108
	v_mul_f32_e32 v111, v111, v115
	ds_write2_b32 v113, v70, v108 offset0:152 offset1:220
	v_cvt_pk_bf16_f32 v70, v110, v110
	v_lshrrev_b32_e32 v70, 16, v70
	v_cvt_pk_bf16_f32 v108, v111, v111
	v_mul_f32_e32 v66, v68, v66
	v_and_or_b32 v70, v108, s63, v70
	ds_write2_b32 v112, v71, v70 offset0:152 offset1:220
	v_mul_f32_e32 v70, v68, v110
	v_cvt_pk_bf16_f32 v66, v66, v66
	v_lshrrev_b32_e32 v66, 16, v66
	v_cvt_pk_bf16_f32 v70, v70, v70
	v_and_or_b32 v66, v70, s63, v66
	v_add_f32_e32 v70, v106, v65
	v_mul_f32_e32 v67, v69, v67
	v_mul_f32_e32 v70, 0x3fb8aa3b, v70
	v_mul_f32_e32 v71, v69, v111
	ds_write_b32 v74, v66 offset:34828
	v_exp_f32_e32 v70, v70
	v_cvt_pk_bf16_f32 v66, v67, v67
	v_lshrrev_b32_e32 v66, 16, v66
	v_cvt_pk_bf16_f32 v67, v71, v71
	v_add_f32_e32 v71, v107, v64
	v_and_or_b32 v66, v67, s63, v66
	v_mul_f32_e32 v71, 0x3fb8aa3b, v71
	ds_write_b32 v74, v66 offset:34972
	v_rcp_f32_e32 v66, v70
	v_exp_f32_e32 v71, v71
	v_lshlrev_b32_e32 v106, 16, v196
	v_add_f32_e32 v104, v104, v65
	v_mul_f32_e32 v66, v66, v106
	v_lshlrev_b32_e32 v106, 16, v195
	v_rcp_f32_e32 v67, v71
	v_mul_f32_e32 v70, v70, v106
	v_and_b32_e32 v106, 0xffff0000, v195
	v_mul_f32_e32 v71, v71, v106
	v_cvt_pk_bf16_f32 v70, v70, v70
	v_mul_f32_e32 v104, 0x3fb8aa3b, v104
	v_and_b32_e32 v107, 0xffff0000, v196
	v_lshrrev_b32_e32 v70, 16, v70
	v_cvt_pk_bf16_f32 v71, v71, v71
	v_exp_f32_e32 v104, v104
	v_mul_f32_e32 v67, v67, v107
	v_and_or_b32 v70, v71, s63, v70
	v_cvt_pk_bf16_f32 v71, v66, v66
	v_lshrrev_b32_e32 v71, 16, v71
	v_cvt_pk_bf16_f32 v106, v67, v67
	v_and_or_b32 v71, v106, s63, v71
	v_add_f32_e32 v105, v105, v64
	v_rcp_f32_e32 v106, v104
	v_mul_f32_e32 v105, 0x3fb8aa3b, v105
	v_exp_f32_e32 v105, v105
	v_lshlrev_b32_e32 v108, 16, v194
	v_mul_f32_e32 v106, v106, v108
	v_lshlrev_b32_e32 v108, 16, v193
	v_mul_f32_e32 v104, v104, v108
	v_and_b32_e32 v108, 0xffff0000, v193
	v_rcp_f32_e32 v107, v105
	v_mul_f32_e32 v105, v105, v108
	v_cvt_pk_bf16_f32 v104, v104, v104
	v_lshrrev_b32_e32 v104, 16, v104
	v_cvt_pk_bf16_f32 v105, v105, v105
	v_and_b32_e32 v109, 0xffff0000, v194
	v_and_or_b32 v104, v105, s63, v104
	v_add_u32_e32 v105, 0x800, v137
	v_mul_f32_e32 v107, v107, v109
	ds_write2_b32 v105, v70, v104 offset0:32 offset1:100
	v_cvt_pk_bf16_f32 v70, v106, v106
	v_lshrrev_b32_e32 v70, 16, v70
	v_cvt_pk_bf16_f32 v104, v107, v107
	v_mul_f32_e32 v66, v68, v66
	v_and_or_b32 v70, v104, s63, v70
	v_add_u32_e32 v104, 0x4c00, v137
	ds_write2_b32 v104, v71, v70 offset0:32 offset1:100
	v_mul_f32_e32 v70, v68, v106
	v_cvt_pk_bf16_f32 v66, v66, v66
	v_lshrrev_b32_e32 v66, 16, v66
	v_cvt_pk_bf16_f32 v70, v70, v70
	v_and_or_b32 v66, v70, s63, v66
	v_add_f32_e32 v70, v102, v65
	v_mul_f32_e32 v67, v69, v67
	v_mul_f32_e32 v70, 0x3fb8aa3b, v70
	v_mul_f32_e32 v71, v69, v107
	ds_write_b32 v74, v66 offset:34832
	v_exp_f32_e32 v70, v70
	v_cvt_pk_bf16_f32 v66, v67, v67
	v_lshrrev_b32_e32 v66, 16, v66
	v_cvt_pk_bf16_f32 v67, v71, v71
	v_add_f32_e32 v71, v103, v64
	v_and_or_b32 v66, v67, s63, v66
	v_mul_f32_e32 v71, 0x3fb8aa3b, v71
	ds_write_b32 v74, v66 offset:34976
	v_rcp_f32_e32 v66, v70
	v_exp_f32_e32 v71, v71
	v_lshlrev_b32_e32 v102, 16, v190
	v_add_f32_e32 v100, v100, v65
	v_mul_f32_e32 v66, v66, v102
	v_lshlrev_b32_e32 v102, 16, v189
	v_rcp_f32_e32 v67, v71
	v_mul_f32_e32 v70, v70, v102
	v_and_b32_e32 v102, 0xffff0000, v189
	v_mul_f32_e32 v71, v71, v102
	v_cvt_pk_bf16_f32 v70, v70, v70
	v_mul_f32_e32 v100, 0x3fb8aa3b, v100
	v_and_b32_e32 v103, 0xffff0000, v190
	v_lshrrev_b32_e32 v70, 16, v70
	v_cvt_pk_bf16_f32 v71, v71, v71
	v_exp_f32_e32 v100, v100
	v_mul_f32_e32 v67, v67, v103
	v_and_or_b32 v70, v71, s63, v70
	v_cvt_pk_bf16_f32 v71, v66, v66
	v_lshrrev_b32_e32 v71, 16, v71
	v_cvt_pk_bf16_f32 v102, v67, v67
	v_and_or_b32 v71, v102, s63, v71
	v_add_f32_e32 v101, v101, v64
	v_rcp_f32_e32 v102, v100
	v_mul_f32_e32 v101, 0x3fb8aa3b, v101
	v_exp_f32_e32 v101, v101
	s_waitcnt vmcnt(19)
	v_lshlrev_b32_e32 v106, 16, v198
	v_mul_f32_e32 v102, v102, v106
	s_waitcnt vmcnt(18)
	v_lshlrev_b32_e32 v106, 16, v197
	v_mul_f32_e32 v100, v100, v106
	v_and_b32_e32 v106, 0xffff0000, v197
	v_rcp_f32_e32 v103, v101
	v_mul_f32_e32 v101, v101, v106
	v_cvt_pk_bf16_f32 v100, v100, v100
	v_lshrrev_b32_e32 v100, 16, v100
	v_cvt_pk_bf16_f32 v101, v101, v101
	v_and_b32_e32 v107, 0xffff0000, v198
	v_and_or_b32 v100, v101, s63, v100
	v_mul_f32_e32 v103, v103, v107
	ds_write2_b32 v105, v70, v100 offset0:168 offset1:236
	v_cvt_pk_bf16_f32 v70, v102, v102
	v_lshrrev_b32_e32 v70, 16, v70
	v_cvt_pk_bf16_f32 v100, v103, v103
	v_mul_f32_e32 v66, v68, v66
	v_and_or_b32 v70, v100, s63, v70
	ds_write2_b32 v104, v71, v70 offset0:168 offset1:236
	v_mul_f32_e32 v70, v68, v102
	v_cvt_pk_bf16_f32 v66, v66, v66
	v_lshrrev_b32_e32 v66, 16, v66
	v_cvt_pk_bf16_f32 v70, v70, v70
	v_and_or_b32 v66, v70, s63, v66
	v_add_f32_e32 v70, v98, v65
	v_mul_f32_e32 v67, v69, v67
	v_mul_f32_e32 v70, 0x3fb8aa3b, v70
	v_mul_f32_e32 v71, v69, v103
	ds_write_b32 v74, v66 offset:34836
	v_exp_f32_e32 v70, v70
	v_cvt_pk_bf16_f32 v66, v67, v67
	v_lshrrev_b32_e32 v66, 16, v66
	v_cvt_pk_bf16_f32 v67, v71, v71
	v_add_f32_e32 v71, v99, v64
	v_and_or_b32 v66, v67, s63, v66
	v_mul_f32_e32 v71, 0x3fb8aa3b, v71
	ds_write_b32 v74, v66 offset:34980
	v_rcp_f32_e32 v66, v70
	v_exp_f32_e32 v71, v71
	s_waitcnt vmcnt(15)
	v_lshlrev_b32_e32 v98, 16, v192
	v_add_f32_e32 v96, v96, v65
	v_mul_f32_e32 v66, v66, v98
	s_waitcnt vmcnt(14)
	v_lshlrev_b32_e32 v98, 16, v191
	v_rcp_f32_e32 v67, v71
	v_mul_f32_e32 v70, v70, v98
	v_and_b32_e32 v98, 0xffff0000, v191
	v_mul_f32_e32 v71, v71, v98
	v_cvt_pk_bf16_f32 v70, v70, v70
	v_mul_f32_e32 v96, 0x3fb8aa3b, v96
	v_and_b32_e32 v99, 0xffff0000, v192
	v_lshrrev_b32_e32 v70, 16, v70
	v_cvt_pk_bf16_f32 v71, v71, v71
	v_exp_f32_e32 v96, v96
	v_mul_f32_e32 v67, v67, v99
	v_and_or_b32 v70, v71, s63, v70
	v_cvt_pk_bf16_f32 v71, v66, v66
	v_lshrrev_b32_e32 v71, 16, v71
	v_cvt_pk_bf16_f32 v98, v67, v67
	v_and_or_b32 v71, v98, s63, v71
	v_add_f32_e32 v97, v97, v64
	v_rcp_f32_e32 v98, v96
	v_mul_f32_e32 v97, 0x3fb8aa3b, v97
	v_exp_f32_e32 v97, v97
	s_waitcnt vmcnt(11)
	v_lshlrev_b32_e32 v100, 16, v188
	v_mul_f32_e32 v98, v98, v100
	s_waitcnt vmcnt(10)
	v_lshlrev_b32_e32 v100, 16, v187
	v_mul_f32_e32 v96, v96, v100
	v_and_b32_e32 v100, 0xffff0000, v187
	v_rcp_f32_e32 v99, v97
	v_mul_f32_e32 v97, v97, v100
	v_cvt_pk_bf16_f32 v96, v96, v96
	v_lshrrev_b32_e32 v96, 16, v96
	v_cvt_pk_bf16_f32 v97, v97, v97
	v_and_b32_e32 v101, 0xffff0000, v188
	v_and_or_b32 v96, v97, s63, v96
	v_add_u32_e32 v97, 0xc00, v137
	v_mul_f32_e32 v99, v99, v101
	ds_write2_b32 v97, v70, v96 offset0:48 offset1:116
	v_cvt_pk_bf16_f32 v70, v98, v98
	v_lshrrev_b32_e32 v70, 16, v70
	v_cvt_pk_bf16_f32 v96, v99, v99
	v_mul_f32_e32 v66, v68, v66
	v_and_or_b32 v70, v96, s63, v70
	v_add_u32_e32 v96, 0x5000, v137
	ds_write2_b32 v96, v71, v70 offset0:48 offset1:116
	v_mul_f32_e32 v70, v68, v98
	v_cvt_pk_bf16_f32 v66, v66, v66
	v_lshrrev_b32_e32 v66, 16, v66
	v_cvt_pk_bf16_f32 v70, v70, v70
	v_and_or_b32 v66, v70, s63, v66
	v_add_f32_e32 v70, v94, v65
	v_mul_f32_e32 v67, v69, v67
	v_mul_f32_e32 v70, 0x3fb8aa3b, v70
	v_mul_f32_e32 v71, v69, v99
	ds_write_b32 v74, v66 offset:34840
	v_exp_f32_e32 v70, v70
	v_cvt_pk_bf16_f32 v66, v67, v67
	v_lshrrev_b32_e32 v66, 16, v66
	v_cvt_pk_bf16_f32 v67, v71, v71
	v_add_f32_e32 v71, v95, v64
	v_and_or_b32 v66, v67, s63, v66
	v_mul_f32_e32 v71, 0x3fb8aa3b, v71
	ds_write_b32 v74, v66 offset:34984
	v_rcp_f32_e32 v66, v70
	v_exp_f32_e32 v71, v71
	s_waitcnt vmcnt(7)
	v_lshlrev_b32_e32 v94, 16, v186
	v_add_f32_e32 v65, v92, v65
	v_mul_f32_e32 v66, v66, v94
	s_waitcnt vmcnt(6)
	v_lshlrev_b32_e32 v94, 16, v185
	v_mul_f32_e32 v65, 0x3fb8aa3b, v65
	v_rcp_f32_e32 v67, v71
	v_mul_f32_e32 v70, v70, v94
	v_and_b32_e32 v94, 0xffff0000, v185
	v_exp_f32_e32 v65, v65
	v_mul_f32_e32 v71, v71, v94
	v_cvt_pk_bf16_f32 v70, v70, v70
	v_and_b32_e32 v95, 0xffff0000, v186
	v_lshrrev_b32_e32 v70, 16, v70
	v_cvt_pk_bf16_f32 v71, v71, v71
	v_mul_f32_e32 v67, v67, v95
	v_and_or_b32 v70, v71, s63, v70
	v_add_f32_e32 v64, v93, v64
	v_rcp_f32_e32 v92, v65
	v_cvt_pk_bf16_f32 v71, v66, v66
	v_mul_f32_e32 v64, 0x3fb8aa3b, v64
	v_lshrrev_b32_e32 v71, 16, v71
	v_cvt_pk_bf16_f32 v94, v67, v67
	v_exp_f32_e32 v64, v64
	v_and_or_b32 v71, v94, s63, v71
	s_waitcnt vmcnt(3)
	v_lshlrev_b32_e32 v94, 16, v184
	v_mul_f32_e32 v92, v92, v94
	s_waitcnt vmcnt(2)
	v_lshlrev_b32_e32 v94, 16, v183
	v_mul_f32_e32 v65, v65, v94
	v_and_b32_e32 v94, 0xffff0000, v183
	v_rcp_f32_e32 v93, v64
	v_mul_f32_e32 v64, v64, v94
	v_cvt_pk_bf16_f32 v65, v65, v65
	v_lshrrev_b32_e32 v65, 16, v65
	v_cvt_pk_bf16_f32 v64, v64, v64
	v_and_b32_e32 v95, 0xffff0000, v184
	v_and_or_b32 v64, v64, s63, v65
	v_mul_f32_e32 v93, v93, v95
	ds_write2_b32 v97, v70, v64 offset0:184 offset1:252
	v_cvt_pk_bf16_f32 v64, v92, v92
	v_lshrrev_b32_e32 v64, 16, v64
	v_cvt_pk_bf16_f32 v65, v93, v93
	v_mul_f32_e32 v66, v68, v66
	v_and_or_b32 v64, v65, s63, v64
	ds_write2_b32 v96, v71, v64 offset0:184 offset1:252
	v_mul_f32_e32 v64, v68, v92
	v_cvt_pk_bf16_f32 v66, v66, v66
	v_lshrrev_b32_e32 v66, 16, v66
	v_cvt_pk_bf16_f32 v64, v64, v64
	v_mul_f32_e32 v67, v69, v67
	v_and_or_b32 v64, v64, s63, v66
	v_mul_f32_e32 v65, v69, v93
	ds_write_b32 v74, v64 offset:34844
	v_cvt_pk_bf16_f32 v64, v67, v67
	v_lshrrev_b32_e32 v64, 16, v64
	v_cvt_pk_bf16_f32 v65, v65, v65
	v_and_or_b32 v64, v65, s63, v64
	v_add_u32_e32 v104, s71, v131
	ds_write_b32 v74, v64 offset:34988
	s_waitcnt lgkmcnt(0)
	s_barrier
	ds_read_b128 v[64:67], v104
	ds_read_b128 v[68:71], v135 offset:17408
	ds_read_b128 v[92:95], v104 offset:64
	ds_read_b128 v[96:99], v135 offset:17472
	ds_read_b128 v[106:109], v135 offset:21760
	ds_read_b128 v[110:113], v135 offset:21824
	s_waitcnt lgkmcnt(4)
	v_mfma_f32_16x16x32_bf16 v[100:103], v[64:67], v[68:71], 0
	ds_read_b128 v[114:117], v104 offset:4352
	ds_read_b128 v[118:121], v104 offset:4416
	v_add_u32_e32 v105, s69, v130
	v_add_u32_e32 v201, s70, v130
	s_waitcnt lgkmcnt(3)
	v_mfma_f32_16x16x32_bf16 v[64:67], v[64:67], v[106:109], 0
	s_sub_i32 s73, s73, 64
	v_mfma_f32_16x16x32_bf16 v[100:103], v[92:95], v[96:99], v[100:103]
	s_waitcnt lgkmcnt(2)
	v_mfma_f32_16x16x32_bf16 v[64:67], v[92:95], v[110:113], v[64:67]
	ds_read_b128 v[92:95], v104 offset:128
	s_waitcnt lgkmcnt(2)
	v_mfma_f32_16x16x32_bf16 v[68:71], v[114:117], v[68:71], 0
	v_mfma_f32_16x16x32_bf16 v[106:109], v[114:117], v[106:109], 0
	s_waitcnt lgkmcnt(1)
	v_mfma_f32_16x16x32_bf16 v[68:71], v[118:121], v[96:99], v[68:71]
	v_mfma_f32_16x16x32_bf16 v[96:99], v[118:121], v[110:113], v[106:109]
	s_nop 4
	ds_read_b128 v[106:109], v135 offset:17536
	ds_read_b128 v[110:113], v104 offset:192
	ds_read_b128 v[114:117], v135 offset:17600
	ds_read_b128 v[118:121], v135 offset:21888
	ds_read_b128 v[184:187], v135 offset:21952
	s_waitcnt lgkmcnt(4)
	v_mfma_f32_16x16x32_bf16 v[100:103], v[92:95], v[106:109], v[100:103]
	s_waitcnt lgkmcnt(1)
	v_mfma_f32_16x16x32_bf16 v[64:67], v[92:95], v[118:121], v[64:67]
	ds_read_b128 v[92:95], v104 offset:4480
	ds_read_b128 v[188:191], v104 offset:4544
	s_waitcnt lgkmcnt(0)
	s_barrier
	v_mfma_f32_16x16x32_bf16 v[68:71], v[92:95], v[106:109], v[68:71]
	v_add_u32_e32 v106, v134, v138
	v_add_u32_e32 v107, s74, v139
	v_mfma_f32_16x16x32_bf16 v[92:95], v[92:95], v[118:121], v[96:99]
	v_add_u32_e32 v199, 18, v107
	s_add_i32 s74, s74, 64
	s_cmpk_lg_i32 s74, 0x200
	v_mfma_f32_16x16x32_bf16 v[96:99], v[110:113], v[114:117], v[100:103]
	v_mfma_f32_16x16x32_bf16 v[64:67], v[110:113], v[184:187], v[64:67]
	v_mfma_f32_16x16x32_bf16 v[68:71], v[188:191], v[114:117], v[68:71]
	s_nop 5
	v_cvt_pk_bf16_f32 v96, v96, v96
	v_lshrrev_b32_e32 v96, 16, v96
	v_cndmask_b32_e64 v96, v96, 0, s[14:15]
	ds_write_b16 v141, v96 offset:17408
	v_cvt_pk_bf16_f32 v96, v97, v97
	v_lshrrev_b32_e32 v96, 16, v96
	v_cndmask_b32_e64 v96, v96, 0, s[16:17]
	ds_write_b16 v141, v96 offset:17552
	v_cvt_pk_bf16_f32 v96, v98, v98
	v_lshrrev_b32_e32 v96, 16, v96
	v_cndmask_b32_e64 v96, v96, 0, s[18:19]
	ds_write_b16 v141, v96 offset:17696
	v_cvt_pk_bf16_f32 v96, v99, v99
	v_lshrrev_b32_e32 v96, 16, v96
	v_cndmask_b32_e64 v96, v96, 0, s[20:21]
	ds_write_b16 v141, v96 offset:17840
	v_cvt_pk_bf16_f32 v64, v64, v64
	v_lshrrev_b32_e32 v64, 16, v64
	v_cndmask_b32_e64 v64, v64, 0, s[22:23]
	ds_write_b16 v141, v64 offset:17440
	v_cvt_pk_bf16_f32 v64, v65, v65
	v_lshrrev_b32_e32 v64, 16, v64
	v_cndmask_b32_e64 v64, v64, 0, s[24:25]
	ds_write_b16 v141, v64 offset:17584
	v_cvt_pk_bf16_f32 v64, v66, v66
	v_lshrrev_b32_e32 v64, 16, v64
	v_cndmask_b32_e64 v64, v64, 0, s[26:27]
	ds_write_b16 v141, v64 offset:17728
	v_cvt_pk_bf16_f32 v64, v67, v67
	v_lshrrev_b32_e32 v64, 16, v64
	v_cndmask_b32_e64 v64, v64, 0, s[28:29]
	ds_write_b16 v141, v64 offset:17872
	v_cvt_pk_bf16_f32 v64, v68, v68
	v_lshrrev_b32_e32 v64, 16, v64
	v_cndmask_b32_e64 v64, v64, 0, s[30:31]
	ds_write_b16 v141, v64 offset:19712
	v_cvt_pk_bf16_f32 v64, v69, v69
	v_lshrrev_b32_e32 v64, 16, v64
	v_cndmask_b32_e64 v64, v64, 0, s[34:35]
	ds_write_b16 v141, v64 offset:19856
	v_cvt_pk_bf16_f32 v64, v70, v70
	v_lshrrev_b32_e32 v64, 16, v64
	v_cndmask_b32_e64 v64, v64, 0, s[36:37]
	v_mfma_f32_16x16x32_bf16 v[92:95], v[188:191], v[184:187], v[92:95]
	ds_write_b16 v141, v64 offset:20000
	v_cvt_pk_bf16_f32 v64, v71, v71
	v_lshrrev_b32_e32 v64, 16, v64
	v_cndmask_b32_e64 v64, v64, 0, s[38:39]
	ds_write_b16 v141, v64 offset:20144
	s_nop 1
	s_nop 0
	v_cvt_pk_bf16_f32 v64, v92, v92
	v_lshrrev_b32_e32 v64, 16, v64
	v_cndmask_b32_e64 v64, v64, 0, s[14:15]
	ds_write_b16 v141, v64 offset:19744
	v_cvt_pk_bf16_f32 v64, v93, v93
	v_lshrrev_b32_e32 v64, 16, v64
	v_cndmask_b32_e64 v64, v64, 0, s[40:41]
	ds_write_b16 v141, v64 offset:19888
	v_cvt_pk_bf16_f32 v64, v94, v94
	v_lshrrev_b32_e32 v64, 16, v64
	v_cndmask_b32_e64 v64, v64, 0, s[42:43]
	ds_write_b16 v141, v64 offset:20032
	v_cvt_pk_bf16_f32 v64, v95, v95
	v_lshrrev_b32_e32 v64, 16, v64
	v_cndmask_b32_e64 v64, v64, 0, s[44:45]
	ds_write_b16 v141, v64 offset:20176
	v_cvt_pk_bf16_f32 v64, v24, v24
	ds_write_b16_d16_hi v106, v64 offset:62464
	v_cvt_pk_bf16_f32 v64, v25, v25
	ds_write_b16_d16_hi v106, v64 offset:62736
	v_cvt_pk_bf16_f32 v64, v26, v26
	ds_write_b16_d16_hi v106, v64 offset:63008
	v_cvt_pk_bf16_f32 v64, v27, v27
	ds_write_b16_d16_hi v106, v64 offset:63280
	v_cvt_pk_bf16_f32 v64, v4, v4
	ds_write_b16_d16_hi v106, v64 offset:62496
	v_cvt_pk_bf16_f32 v64, v5, v5
	ds_write_b16_d16_hi v106, v64 offset:62768
	v_cvt_pk_bf16_f32 v64, v6, v6
	ds_write_b16_d16_hi v106, v64 offset:63040
	v_cvt_pk_bf16_f32 v64, v7, v7
	ds_write_b16_d16_hi v106, v64 offset:63312
	v_cvt_pk_bf16_f32 v64, v8, v8
	ds_write_b16_d16_hi v106, v64 offset:62528
	v_cvt_pk_bf16_f32 v64, v9, v9
	ds_write_b16_d16_hi v106, v64 offset:62800
	v_cvt_pk_bf16_f32 v64, v10, v10
	ds_write_b16_d16_hi v106, v64 offset:63072
	v_cvt_pk_bf16_f32 v64, v11, v11
	ds_write_b16_d16_hi v106, v64 offset:63344
	v_cvt_pk_bf16_f32 v64, v0, v0
	ds_write_b16_d16_hi v106, v64 offset:62560
	v_cvt_pk_bf16_f32 v64, v1, v1
	ds_write_b16_d16_hi v106, v64 offset:62832
	v_cvt_pk_bf16_f32 v64, v2, v2
	ds_write_b16_d16_hi v106, v64 offset:63104
	v_cvt_pk_bf16_f32 v64, v3, v3
	ds_write_b16_d16_hi v106, v64 offset:63376
	v_cvt_pk_bf16_f32 v64, v12, v12
	ds_write_b16_d16_hi v142, v64 offset:62464
	v_cvt_pk_bf16_f32 v64, v13, v13
	ds_write_b16_d16_hi v143, v64 offset:62464
	v_cvt_pk_bf16_f32 v64, v14, v14
	ds_write_b16_d16_hi v145, v64 offset:62464
	v_cvt_pk_bf16_f32 v64, v15, v15
	ds_write_b16_d16_hi v146, v64 offset:62464
	v_cvt_pk_bf16_f32 v64, v16, v16
	ds_write_b16_d16_hi v142, v64 offset:62496
	v_cvt_pk_bf16_f32 v64, v17, v17
	ds_write_b16_d16_hi v143, v64 offset:62496
	v_cvt_pk_bf16_f32 v64, v18, v18
	ds_write_b16_d16_hi v145, v64 offset:62496
	v_cvt_pk_bf16_f32 v64, v19, v19
	ds_write_b16_d16_hi v146, v64 offset:62496
	v_cvt_pk_bf16_f32 v64, v20, v20
	ds_write_b16_d16_hi v142, v64 offset:62528
	v_cvt_pk_bf16_f32 v64, v21, v21
	ds_write_b16_d16_hi v143, v64 offset:62528
	v_cvt_pk_bf16_f32 v64, v22, v22
	ds_write_b16_d16_hi v145, v64 offset:62528
	v_cvt_pk_bf16_f32 v64, v23, v23
	ds_write_b16_d16_hi v146, v64 offset:62528
	v_cvt_pk_bf16_f32 v64, v40, v40
	ds_write_b16_d16_hi v142, v64 offset:62560
	v_cvt_pk_bf16_f32 v64, v41, v41
	ds_write_b16_d16_hi v143, v64 offset:62560
	v_cvt_pk_bf16_f32 v64, v42, v42
	ds_write_b16_d16_hi v145, v64 offset:62560
	v_cvt_pk_bf16_f32 v64, v43, v43
	ds_write_b16_d16_hi v146, v64 offset:62560
	v_lshlrev_b32_e32 v64, 16, v166
	v_lshlrev_b32_e32 v65, 16, v170
	v_lshlrev_b32_e32 v66, 16, v172
	v_lshlrev_b32_e32 v67, 16, v174
	v_lshlrev_b32_e32 v68, 16, v176
	v_lshlrev_b32_e32 v69, 16, v178
	v_lshlrev_b32_e32 v70, 16, v180
	s_waitcnt vmcnt(1)
	v_lshlrev_b32_e32 v71, 16, v182
	v_or_b32_sdwa v64, v64, v165 dst_sel:DWORD dst_unused:UNUSED_PAD src0_sel:DWORD src1_sel:WORD_0
	v_or_b32_sdwa v65, v65, v167 dst_sel:DWORD dst_unused:UNUSED_PAD src0_sel:DWORD src1_sel:WORD_0
	v_or_b32_sdwa v66, v66, v171 dst_sel:DWORD dst_unused:UNUSED_PAD src0_sel:DWORD src1_sel:WORD_0
	v_or_b32_sdwa v67, v67, v173 dst_sel:DWORD dst_unused:UNUSED_PAD src0_sel:DWORD src1_sel:WORD_0
	v_or_b32_sdwa v68, v68, v175 dst_sel:DWORD dst_unused:UNUSED_PAD src0_sel:DWORD src1_sel:WORD_0
	v_or_b32_sdwa v69, v69, v177 dst_sel:DWORD dst_unused:UNUSED_PAD src0_sel:DWORD src1_sel:WORD_0
	v_or_b32_sdwa v70, v70, v179 dst_sel:DWORD dst_unused:UNUSED_PAD src0_sel:DWORD src1_sel:WORD_0
	v_or_b32_sdwa v71, v71, v181 dst_sel:DWORD dst_unused:UNUSED_PAD src0_sel:DWORD src1_sel:WORD_0
	ds_write_b128 v147, v[64:67] offset:53248
	ds_write_b128 v147, v[68:71] offset:53264
	s_waitcnt lgkmcnt(0)
	s_barrier
	ds_read_b128 v[64:67], v104
	ds_read_b128 v[68:71], v135 offset:62464
	ds_read_b128 v[92:95], v104 offset:64
	ds_read_b128 v[96:99], v135 offset:62528
	ds_read_b128 v[108:111], v136 offset:4352
	ds_read_b128 v[112:115], v136 offset:4416
	s_waitcnt lgkmcnt(4)
	v_mfma_f32_16x16x32_bf16 v[100:103], v[64:67], v[68:71], 0
	ds_read_b128 v[116:119], v104 offset:4352
	ds_read_b128 v[120:123], v104 offset:4416
	v_add_u32_e32 v167, s72, v130
	v_add_u32_e32 v165, s66, v140
	s_waitcnt lgkmcnt(3)
	v_mfma_f32_16x16x32_bf16 v[64:67], v[64:67], v[108:111], 0
	v_add_u32_e32 v200, 0x1fed, v165
	v_subrev_u32_e32 v140, 64, v140
	v_mfma_f32_16x16x32_bf16 v[100:103], v[92:95], v[96:99], v[100:103]
	s_waitcnt lgkmcnt(2)
	v_mfma_f32_16x16x32_bf16 v[64:67], v[92:95], v[112:115], v[64:67]
	ds_read_b128 v[92:95], v104 offset:128
	s_waitcnt lgkmcnt(2)
	v_mfma_f32_16x16x32_bf16 v[68:71], v[116:119], v[68:71], 0
	v_mfma_f32_16x16x32_bf16 v[108:111], v[116:119], v[108:111], 0
	s_waitcnt lgkmcnt(1)
	v_mfma_f32_16x16x32_bf16 v[68:71], v[120:123], v[96:99], v[68:71]
	v_mfma_f32_16x16x32_bf16 v[96:99], v[120:123], v[112:115], v[108:111]
	s_nop 4
	ds_read_b128 v[108:111], v135 offset:62592
	ds_read_b128 v[112:115], v104 offset:192
	ds_read_b128 v[116:119], v135 offset:62656
	ds_read_b128 v[120:123], v136 offset:4480
	ds_read_b128 v[170:173], v136 offset:4544
	s_waitcnt lgkmcnt(4)
	v_mfma_f32_16x16x32_bf16 v[100:103], v[92:95], v[108:111], v[100:103]
	s_waitcnt lgkmcnt(1)
	v_mfma_f32_16x16x32_bf16 v[64:67], v[92:95], v[120:123], v[64:67]
	ds_read_b128 v[92:95], v104 offset:4480
	ds_read_b128 v[174:177], v104 offset:4544
	s_waitcnt lgkmcnt(1)
	v_mfma_f32_16x16x32_bf16 v[68:71], v[92:95], v[108:111], v[68:71]
	v_mfma_f32_16x16x32_bf16 v[92:95], v[92:95], v[120:123], v[96:99]
	v_mfma_f32_16x16x32_bf16 v[96:99], v[112:115], v[116:119], v[100:103]
	s_nop 2
	ds_read_b128 v[100:103], v105 offset:17408
	v_mfma_f32_16x16x32_bf16 v[64:67], v[112:115], v[170:173], v[64:67]
	s_waitcnt lgkmcnt(1)
	v_mfma_f32_16x16x32_bf16 v[68:71], v[174:177], v[116:119], v[68:71]
	ds_read_b128 v[108:111], v167 offset:53248
	ds_read_b128 v[112:115], v105 offset:17472
	ds_read_b128 v[116:119], v167 offset:53312
	v_mfma_f32_16x16x32_bf16 v[92:95], v[174:177], v[170:173], v[92:95]
	ds_read_b128 v[120:123], v167 offset:55552
	ds_read_b128 v[170:173], v167 offset:55616
	s_waitcnt lgkmcnt(4)
	v_mfma_f32_16x16x32_bf16 v[96:99], v[100:103], v[108:111], v[96:99]
	s_waitcnt lgkmcnt(1)
	v_mfma_f32_16x16x32_bf16 v[64:67], v[100:103], v[120:123], v[64:67]
	ds_read_b128 v[100:103], v105 offset:19712
	ds_read_b128 v[174:177], v105 offset:19776
	s_waitcnt lgkmcnt(1)
	v_mfma_f32_16x16x32_bf16 v[92:95], v[100:103], v[120:123], v[92:95]
	v_mfma_f32_16x16x32_bf16 v[68:71], v[100:103], v[108:111], v[68:71]
	v_mfma_f32_16x16x32_bf16 v[108:111], v[112:115], v[116:119], v[96:99]
	v_mfma_f32_16x16x32_bf16 v[112:115], v[112:115], v[170:173], v[64:67]
	s_waitcnt lgkmcnt(0)
	v_mfma_f32_16x16x32_bf16 v[64:67], v[174:177], v[170:173], v[92:95]
	s_nop 2
	v_add_u32_e32 v92, 0x1fff, v165
	v_cndmask_b32_e64 v92, v92, v107, s[6:7]
	v_add_u32_e32 v92, s67, v92
	v_ashrrev_i32_e32 v93, 31, v92
	v_lshlrev_b64 v[92:93], 11, v[92:93]
	v_lshl_add_u64 v[100:101], v[88:89], 0, v[92:93]
	v_cvt_pk_bf16_f32 v92, v108, v108
	global_store_short_d16_hi v[100:101], v92, off
	v_cvt_pk_bf16_f32 v92, v112, v112
	global_store_short_d16_hi v[100:101], v92, off offset:32
	v_add_u32_e32 v92, 1, v107
	v_add_u32_e32 v93, 0x1ffe, v165
	v_cndmask_b32_e64 v92, v93, v92, s[6:7]
	v_add_u32_e32 v92, s67, v92
	v_ashrrev_i32_e32 v93, 31, v92
	v_lshlrev_b64 v[92:93], 11, v[92:93]
	v_lshl_add_u64 v[102:103], v[88:89], 0, v[92:93]
	v_cvt_pk_bf16_f32 v92, v109, v109
	global_store_short_d16_hi v[102:103], v92, off
	v_cvt_pk_bf16_f32 v92, v113, v113
	global_store_short_d16_hi v[102:103], v92, off offset:32
	v_add_u32_e32 v92, 2, v107
	v_add_u32_e32 v93, 0x1ffd, v165
	v_cndmask_b32_e64 v92, v93, v92, s[6:7]
	v_add_u32_e32 v92, s67, v92
	v_ashrrev_i32_e32 v93, 31, v92
	v_lshlrev_b64 v[92:93], 11, v[92:93]
	v_lshl_add_u64 v[98:99], v[88:89], 0, v[92:93]
	v_cvt_pk_bf16_f32 v92, v110, v110
	global_store_short_d16_hi v[98:99], v92, off
	v_cvt_pk_bf16_f32 v92, v114, v114
	global_store_short_d16_hi v[98:99], v92, off offset:32
	v_add_u32_e32 v92, 3, v107
	v_add_u32_e32 v93, 0x1ffc, v165
	v_cndmask_b32_e64 v92, v93, v92, s[6:7]
	v_add_u32_e32 v92, s67, v92
	v_ashrrev_i32_e32 v93, 31, v92
	v_lshlrev_b64 v[92:93], 11, v[92:93]
	v_lshl_add_u64 v[92:93], v[88:89], 0, v[92:93]
	v_cvt_pk_bf16_f32 v94, v111, v111
	global_store_short_d16_hi v[92:93], v94, off
	v_cvt_pk_bf16_f32 v94, v115, v115
	v_mfma_f32_16x16x32_bf16 v[68:71], v[174:177], v[116:119], v[68:71]
	global_store_short_d16_hi v[92:93], v94, off offset:32
	v_add_u32_e32 v94, 16, v107
	v_add_u32_e32 v95, 0x1fef, v165
	v_cndmask_b32_e64 v94, v95, v94, s[6:7]
	v_add_u32_e32 v94, s67, v94
	v_ashrrev_i32_e32 v95, 31, v94
	v_lshlrev_b64 v[94:95], 11, v[94:95]
	s_nop 0
	v_lshl_add_u64 v[94:95], v[88:89], 0, v[94:95]
	v_cvt_pk_bf16_f32 v68, v68, v68
	global_store_short_d16_hi v[94:95], v68, off
	v_cvt_pk_bf16_f32 v64, v64, v64
	global_store_short_d16_hi v[94:95], v64, off offset:32
	v_add_u32_e32 v64, 17, v107
	v_add_u32_e32 v68, 0x1fee, v165
	v_cndmask_b32_e64 v64, v68, v64, s[6:7]
	v_add_u32_e32 v96, s67, v64
	v_ashrrev_i32_e32 v97, 31, v96
	v_lshlrev_b64 v[96:97], 11, v[96:97]
	v_lshl_add_u64 v[96:97], v[88:89], 0, v[96:97]
	v_cvt_pk_bf16_f32 v64, v69, v69
	ds_read2_b32 v[68:69], v148 offset1:16
	global_store_short_d16_hi v[96:97], v64, off
	v_cvt_pk_bf16_f32 v64, v65, v65
	global_store_short_d16_hi v[96:97], v64, off offset:32
	ds_read2_b32 v[64:65], v148 offset0:32 offset1:48
	s_waitcnt lgkmcnt(1)
	v_pk_mul_f32 v[26:27], v[26:27], v[68:69] op_sel_hi:[1,0]
	v_pk_mul_f32 v[24:25], v[24:25], v[68:69] op_sel_hi:[1,0]
	v_pk_mul_f32 v[14:15], v[14:15], v[68:69] op_sel_hi:[1,0]
	v_pk_mul_f32 v[12:13], v[12:13], v[68:69] op_sel_hi:[1,0]
	v_cndmask_b32_e64 v68, v200, v199, s[6:7]
	v_add_u32_e32 v68, s67, v68
	v_mov_b32_e32 v166, v69
	v_ashrrev_i32_e32 v69, 31, v68
	s_waitcnt lgkmcnt(0)
	v_pk_mul_f32 v[10:11], v[10:11], v[64:65] op_sel_hi:[1,0]
	v_pk_mul_f32 v[8:9], v[8:9], v[64:65] op_sel_hi:[1,0]
	v_mov_b32_e32 v198, v65
	v_pk_mul_f32 v[22:23], v[22:23], v[64:65] op_sel_hi:[1,0]
	v_pk_mul_f32 v[20:21], v[20:21], v[64:65] op_sel_hi:[1,0]
	v_lshlrev_b64 v[64:65], 11, v[68:69]
	v_lshl_add_u64 v[64:65], v[88:89], 0, v[64:65]
	v_cvt_pk_bf16_f32 v68, v70, v70
	ds_read_b128 v[108:111], v105 offset:53248
	ds_read_b128 v[112:115], v201 offset:34816
	ds_read_b128 v[116:119], v201 offset:37120
	ds_read_b128 v[120:123], v105 offset:53312
	ds_read_b128 v[170:173], v201 offset:34880
	ds_read_b128 v[174:177], v201 offset:39424
	ds_read_b128 v[178:181], v201 offset:37184
	ds_read_b128 v[182:185], v105 offset:55552
	ds_read_b128 v[186:189], v201 offset:41728
	ds_read_b128 v[190:193], v201 offset:39488
	global_store_short_d16_hi v[64:65], v68, off
	v_cvt_pk_bf16_f32 v66, v66, v66
	global_store_short_d16_hi v[64:65], v66, off offset:32
	v_add_u32_e32 v66, 19, v107
	v_add_u32_e32 v68, 0x1fec, v165
	v_cndmask_b32_e64 v66, v68, v66, s[6:7]
	v_add_u32_e32 v68, s67, v66
	v_ashrrev_i32_e32 v69, 31, v68
	v_lshlrev_b64 v[68:69], 11, v[68:69]
	v_lshl_add_u64 v[68:69], v[88:89], 0, v[68:69]
	v_cvt_pk_bf16_f32 v66, v71, v71
	global_store_short_d16_hi v[68:69], v66, off
	v_cvt_pk_bf16_f32 v66, v67, v67
	global_store_short_d16_hi v[68:69], v66, off offset:32
	v_pk_mul_f32 v[6:7], v[6:7], v[166:167] op_sel_hi:[1,0]
	v_pk_mul_f32 v[4:5], v[4:5], v[166:167] op_sel_hi:[1,0]
	v_pk_mul_f32 v[2:3], v[2:3], v[198:199] op_sel_hi:[1,0]
	v_pk_mul_f32 v[0:1], v[0:1], v[198:199] op_sel_hi:[1,0]
	v_cvt_pk_bf16_f32 v66, v48, v48
	s_waitcnt lgkmcnt(8)
	v_mfma_f32_16x16x32_bf16 v[24:27], v[108:111], v[112:115], v[24:27]
	ds_read_b128 v[194:197], v201 offset:41792
	v_pk_mul_f32 v[18:19], v[18:19], v[166:167] op_sel_hi:[1,0]
	v_pk_mul_f32 v[16:17], v[16:17], v[166:167] op_sel_hi:[1,0]
	s_waitcnt lgkmcnt(8)
	v_mfma_f32_16x16x32_bf16 v[4:7], v[108:111], v[116:119], v[4:7]
	v_mul_f32_e64 v42, v42, v198
	v_mul_f32_e64 v43, v43, v198
	v_pk_mul_f32 v[40:41], v[40:41], v[198:199] op_sel_hi:[1,0]
	s_waitcnt lgkmcnt(5)
	v_mfma_f32_16x16x32_bf16 v[8:11], v[108:111], v[174:177], v[8:11]
	s_waitcnt lgkmcnt(2)
	v_mfma_f32_16x16x32_bf16 v[0:3], v[108:111], v[186:189], v[0:3]
	ds_read_b128 v[108:111], v105 offset:55616
	s_waitcnt lgkmcnt(0)
	s_barrier
	ds_write_b16_d16_hi v106, v66 offset:62464
	v_cvt_pk_bf16_f32 v66, v49, v49
	ds_write_b16_d16_hi v106, v66 offset:62736
	v_cvt_pk_bf16_f32 v66, v50, v50
	ds_write_b16_d16_hi v106, v66 offset:63008
	v_cvt_pk_bf16_f32 v66, v51, v51
	ds_write_b16_d16_hi v106, v66 offset:63280
	v_cvt_pk_bf16_f32 v66, v32, v32
	ds_write_b16_d16_hi v106, v66 offset:62496
	v_cvt_pk_bf16_f32 v66, v33, v33
	ds_write_b16_d16_hi v106, v66 offset:62768
	v_cvt_pk_bf16_f32 v66, v34, v34
	ds_write_b16_d16_hi v106, v66 offset:63040
	v_cvt_pk_bf16_f32 v66, v35, v35
	ds_write_b16_d16_hi v106, v66 offset:63312
	v_cvt_pk_bf16_f32 v66, v36, v36
	ds_write_b16_d16_hi v106, v66 offset:62528
	v_cvt_pk_bf16_f32 v66, v37, v37
	ds_write_b16_d16_hi v106, v66 offset:62800
	v_cvt_pk_bf16_f32 v66, v38, v38
	ds_write_b16_d16_hi v106, v66 offset:63072
	v_cvt_pk_bf16_f32 v66, v39, v39
	ds_write_b16_d16_hi v106, v66 offset:63344
	v_cvt_pk_bf16_f32 v66, v28, v28
	ds_write_b16_d16_hi v106, v66 offset:62560
	v_cvt_pk_bf16_f32 v66, v29, v29
	ds_write_b16_d16_hi v106, v66 offset:62832
	v_cvt_pk_bf16_f32 v66, v30, v30
	ds_write_b16_d16_hi v106, v66 offset:63104
	v_cvt_pk_bf16_f32 v66, v31, v31
	ds_write_b16_d16_hi v106, v66 offset:63376
	v_cvt_pk_bf16_f32 v66, v44, v44
	ds_write_b16_d16_hi v142, v66 offset:62464
	v_cvt_pk_bf16_f32 v66, v45, v45
	ds_write_b16_d16_hi v143, v66 offset:62464
	v_cvt_pk_bf16_f32 v66, v46, v46
	ds_write_b16_d16_hi v145, v66 offset:62464
	v_cvt_pk_bf16_f32 v66, v47, v47
	ds_write_b16_d16_hi v146, v66 offset:62464
	v_cvt_pk_bf16_f32 v66, v52, v52
	ds_write_b16_d16_hi v142, v66 offset:62496
	v_cvt_pk_bf16_f32 v66, v53, v53
	ds_write_b16_d16_hi v143, v66 offset:62496
	v_cvt_pk_bf16_f32 v66, v54, v54
	ds_write_b16_d16_hi v145, v66 offset:62496
	v_cvt_pk_bf16_f32 v66, v55, v55
	ds_write_b16_d16_hi v146, v66 offset:62496
	v_cvt_pk_bf16_f32 v66, v56, v56
	ds_write_b16_d16_hi v142, v66 offset:62528
	v_cvt_pk_bf16_f32 v66, v57, v57
	ds_write_b16_d16_hi v143, v66 offset:62528
	v_cvt_pk_bf16_f32 v66, v58, v58
	ds_write_b16_d16_hi v145, v66 offset:62528
	v_cvt_pk_bf16_f32 v66, v59, v59
	ds_write_b16_d16_hi v146, v66 offset:62528
	v_cvt_pk_bf16_f32 v66, v60, v60
	ds_write_b16_d16_hi v142, v66 offset:62560
	v_cvt_pk_bf16_f32 v66, v61, v61
	ds_write_b16_d16_hi v143, v66 offset:62560
	v_cvt_pk_bf16_f32 v66, v62, v62
	ds_write_b16_d16_hi v145, v66 offset:62560
	v_cvt_pk_bf16_f32 v66, v63, v63
	ds_write_b16_d16_hi v146, v66 offset:62560
	v_lshlrev_b32_e32 v66, 16, v150
	v_mfma_f32_16x16x32_bf16 v[12:15], v[182:185], v[112:115], v[12:15]
	v_or_b32_sdwa v112, v66, v149 dst_sel:DWORD dst_unused:UNUSED_PAD src0_sel:DWORD src1_sel:WORD_0
	v_lshlrev_b32_e32 v66, 16, v152
	v_or_b32_sdwa v113, v66, v151 dst_sel:DWORD dst_unused:UNUSED_PAD src0_sel:DWORD src1_sel:WORD_0
	v_lshlrev_b32_e32 v66, 16, v154
	v_or_b32_sdwa v114, v66, v153 dst_sel:DWORD dst_unused:UNUSED_PAD src0_sel:DWORD src1_sel:WORD_0
	v_lshlrev_b32_e32 v66, 16, v156
	v_or_b32_sdwa v115, v66, v155 dst_sel:DWORD dst_unused:UNUSED_PAD src0_sel:DWORD src1_sel:WORD_0
	v_lshlrev_b32_e32 v66, 16, v158
	v_mfma_f32_16x16x32_bf16 v[16:19], v[182:185], v[116:119], v[16:19]
	v_or_b32_sdwa v116, v66, v157 dst_sel:DWORD dst_unused:UNUSED_PAD src0_sel:DWORD src1_sel:WORD_0
	v_lshlrev_b32_e32 v66, 16, v160
	v_or_b32_sdwa v117, v66, v159 dst_sel:DWORD dst_unused:UNUSED_PAD src0_sel:DWORD src1_sel:WORD_0
	v_lshlrev_b32_e32 v66, 16, v162
	v_or_b32_sdwa v118, v66, v161 dst_sel:DWORD dst_unused:UNUSED_PAD src0_sel:DWORD src1_sel:WORD_0
	s_waitcnt vmcnt(16)
	v_lshlrev_b32_e32 v66, 16, v164
	v_or_b32_sdwa v119, v66, v163 dst_sel:DWORD dst_unused:UNUSED_PAD src0_sel:DWORD src1_sel:WORD_0
	ds_write_b128 v147, v[112:115] offset:53248
	ds_write_b128 v147, v[116:119] offset:53264
	s_waitcnt lgkmcnt(0)
	s_barrier
	ds_read_b128 v[112:115], v104
	v_mfma_f32_16x16x32_bf16 v[20:23], v[182:185], v[174:177], v[20:23]
	v_mfma_f32_16x16x32_bf16 v[40:43], v[182:185], v[186:189], v[40:43]
	v_mfma_f32_16x16x32_bf16 v[24:27], v[120:123], v[170:173], v[24:27]
	v_mfma_f32_16x16x32_bf16 v[4:7], v[120:123], v[178:181], v[4:7]
	v_mfma_f32_16x16x32_bf16 v[8:11], v[120:123], v[190:193], v[8:11]
	v_mfma_f32_16x16x32_bf16 v[0:3], v[120:123], v[194:197], v[0:3]
	v_mfma_f32_16x16x32_bf16 v[12:15], v[108:111], v[170:173], v[12:15]
	v_mfma_f32_16x16x32_bf16 v[16:19], v[108:111], v[178:181], v[16:19]
	v_mfma_f32_16x16x32_bf16 v[20:23], v[108:111], v[190:193], v[20:23]
	v_mfma_f32_16x16x32_bf16 v[40:43], v[108:111], v[194:197], v[40:43]
	ds_read_b128 v[106:109], v135 offset:62464
	ds_read_b128 v[116:119], v104 offset:64
	ds_read_b128 v[120:123], v135 offset:62528
	ds_read_b128 v[154:157], v136 offset:4352
	ds_read_b128 v[158:161], v136 offset:4416
	ds_read_b128 v[162:165], v104 offset:4352
	ds_read_b128 v[170:173], v104 offset:4416
	s_waitcnt lgkmcnt(6)
	v_mfma_f32_16x16x32_bf16 v[150:153], v[112:115], v[106:109], 0
	s_waitcnt lgkmcnt(3)
	v_mfma_f32_16x16x32_bf16 v[110:113], v[112:115], v[154:157], 0
	v_mfma_f32_16x16x32_bf16 v[150:153], v[116:119], v[120:123], v[150:153]
	s_waitcnt lgkmcnt(2)
	v_mfma_f32_16x16x32_bf16 v[110:113], v[116:119], v[158:161], v[110:113]
	ds_read_b128 v[114:117], v104 offset:128
	s_waitcnt lgkmcnt(2)
	v_mfma_f32_16x16x32_bf16 v[106:109], v[162:165], v[106:109], 0
	v_mfma_f32_16x16x32_bf16 v[154:157], v[162:165], v[154:157], 0
	s_waitcnt lgkmcnt(1)
	v_mfma_f32_16x16x32_bf16 v[106:109], v[170:173], v[120:123], v[106:109]
	v_mfma_f32_16x16x32_bf16 v[118:121], v[170:173], v[158:161], v[154:157]
	s_nop 4
	ds_read_b128 v[154:157], v135 offset:62592
	ds_read_b128 v[158:161], v104 offset:192
	ds_read_b128 v[162:165], v135 offset:62656
	ds_read_b128 v[170:173], v136 offset:4480
	ds_read_b128 v[174:177], v136 offset:4544
	s_waitcnt lgkmcnt(4)
	v_mfma_f32_16x16x32_bf16 v[150:153], v[114:117], v[154:157], v[150:153]
	s_waitcnt lgkmcnt(1)
	v_mfma_f32_16x16x32_bf16 v[110:113], v[114:117], v[170:173], v[110:113]
	ds_read_b128 v[114:117], v104 offset:4480
	ds_read_b128 v[178:181], v104 offset:4544
	s_waitcnt lgkmcnt(1)
	v_mfma_f32_16x16x32_bf16 v[106:109], v[114:117], v[154:157], v[106:109]
	v_mfma_f32_16x16x32_bf16 v[114:117], v[114:117], v[170:173], v[118:121]
	v_mfma_f32_16x16x32_bf16 v[118:121], v[158:161], v[162:165], v[150:153]
	s_nop 2
	ds_read_b128 v[150:153], v105 offset:17408
	v_mfma_f32_16x16x32_bf16 v[110:113], v[158:161], v[174:177], v[110:113]
	s_waitcnt lgkmcnt(1)
	v_mfma_f32_16x16x32_bf16 v[106:109], v[178:181], v[162:165], v[106:109]
	ds_read_b128 v[154:157], v167 offset:53248
	ds_read_b128 v[158:161], v105 offset:17472
	ds_read_b128 v[162:165], v167 offset:53312
	v_mfma_f32_16x16x32_bf16 v[114:117], v[178:181], v[174:177], v[114:117]
	ds_read_b128 v[170:173], v167 offset:55552
	ds_read_b128 v[174:177], v167 offset:55616
	s_waitcnt lgkmcnt(4)
	v_mfma_f32_16x16x32_bf16 v[118:121], v[150:153], v[154:157], v[118:121]
	s_waitcnt lgkmcnt(1)
	v_mfma_f32_16x16x32_bf16 v[110:113], v[150:153], v[170:173], v[110:113]
	ds_read_b128 v[150:153], v105 offset:19712
	ds_read_b128 v[178:181], v105 offset:19776
	v_mfma_f32_16x16x32_bf16 v[118:121], v[158:161], v[162:165], v[118:121]
	s_waitcnt lgkmcnt(2)
	v_mfma_f32_16x16x32_bf16 v[110:113], v[158:161], v[174:177], v[110:113]
	s_waitcnt lgkmcnt(1)
	v_mfma_f32_16x16x32_bf16 v[106:109], v[150:153], v[154:157], v[106:109]
	s_nop 3
	v_cvt_pk_bf16_f32 v66, v118, v118
	global_store_short_d16_hi v[100:101], v66, off offset:128
	v_cvt_pk_bf16_f32 v66, v110, v110
	global_store_short_d16_hi v[100:101], v66, off offset:160
	v_cvt_pk_bf16_f32 v66, v119, v119
	global_store_short_d16_hi v[102:103], v66, off offset:128
	v_cvt_pk_bf16_f32 v66, v111, v111
	global_store_short_d16_hi v[102:103], v66, off offset:160
	v_cvt_pk_bf16_f32 v66, v120, v120
	global_store_short_d16_hi v[98:99], v66, off offset:128
	v_cvt_pk_bf16_f32 v70, v112, v112
	ds_read2_b32 v[66:67], v148 offset1:16
	v_mfma_f32_16x16x32_bf16 v[114:117], v[150:153], v[170:173], v[114:117]
	global_store_short_d16_hi v[98:99], v70, off offset:160
	ds_read_b128 v[98:101], v105 offset:53248
	v_cvt_pk_bf16_f32 v70, v121, v121
	s_waitcnt lgkmcnt(2)
	v_mfma_f32_16x16x32_bf16 v[106:109], v[178:181], v[162:165], v[106:109]
	global_store_short_d16_hi v[92:93], v70, off offset:128
	ds_read2_b32 v[70:71], v148 offset0:32 offset1:48
	s_waitcnt lgkmcnt(2)
	v_pk_mul_f32 v[50:51], v[50:51], v[66:67] op_sel_hi:[1,0]
	v_mfma_f32_16x16x32_bf16 v[114:117], v[178:181], v[174:177], v[114:117]
	v_mul_f32_e64 v48, v48, v66
	v_mul_f32_e64 v49, v49, v66
	ds_read_b128 v[118:121], v201 offset:34816
	v_pk_mul_f32 v[46:47], v[46:47], v[66:67] op_sel_hi:[1,0]
	v_pk_mul_f32 v[44:45], v[44:45], v[66:67] op_sel_hi:[1,0]
	ds_read_b128 v[150:153], v201 offset:37120
	ds_read_b128 v[154:157], v105 offset:53312
	ds_read_b128 v[158:161], v201 offset:34880
	ds_read_b128 v[162:165], v201 offset:39424
	ds_read_b128 v[170:173], v201 offset:37184
	ds_read_b128 v[174:177], v105 offset:55552
	ds_read_b128 v[178:181], v201 offset:41728
	ds_read_b128 v[182:185], v201 offset:39488
	v_cvt_pk_bf16_f32 v66, v113, v113
	global_store_short_d16_hi v[92:93], v66, off offset:160
	v_mov_b32_e32 v102, v67
	s_waitcnt lgkmcnt(9)
	v_mov_b32_e32 v104, v71
	v_cvt_pk_bf16_f32 v66, v106, v106
	v_pk_mul_f32 v[34:35], v[34:35], v[102:103] op_sel_hi:[1,0]
	v_pk_mul_f32 v[32:33], v[32:33], v[102:103] op_sel_hi:[1,0]
	v_pk_mul_f32 v[38:39], v[38:39], v[70:71] op_sel_hi:[1,0]
	v_pk_mul_f32 v[36:37], v[36:37], v[70:71] op_sel_hi:[1,0]
	v_pk_mul_f32 v[30:31], v[30:31], v[104:105] op_sel_hi:[1,0]
	v_pk_mul_f32 v[28:29], v[28:29], v[104:105] op_sel_hi:[1,0]
	global_store_short_d16_hi v[94:95], v66, off offset:128
	s_waitcnt lgkmcnt(8)
	v_mfma_f32_16x16x32_bf16 v[48:51], v[98:101], v[118:121], v[48:51]
	ds_read_b128 v[186:189], v201 offset:41792
	v_cvt_pk_bf16_f32 v66, v114, v114
	global_store_short_d16_hi v[94:95], v66, off offset:160
	s_waitcnt lgkmcnt(8)
	v_mfma_f32_16x16x32_bf16 v[32:35], v[98:101], v[150:153], v[32:35]
	v_cvt_pk_bf16_f32 v66, v107, v107
	global_store_short_d16_hi v[96:97], v66, off offset:128
	s_waitcnt lgkmcnt(5)
	v_mfma_f32_16x16x32_bf16 v[36:39], v[98:101], v[162:165], v[36:39]
	v_pk_mul_f32 v[54:55], v[54:55], v[102:103] op_sel_hi:[1,0]
	v_pk_mul_f32 v[52:53], v[52:53], v[102:103] op_sel_hi:[1,0]
	s_waitcnt lgkmcnt(2)
	v_mfma_f32_16x16x32_bf16 v[28:31], v[98:101], v[178:181], v[28:31]
	ds_read_b128 v[98:101], v105 offset:55616
	v_pk_mul_f32 v[58:59], v[58:59], v[70:71] op_sel_hi:[1,0]
	v_pk_mul_f32 v[56:57], v[56:57], v[70:71] op_sel_hi:[1,0]
	v_pk_mul_f32 v[62:63], v[62:63], v[104:105] op_sel_hi:[1,0]
	v_pk_mul_f32 v[60:61], v[60:61], v[104:105] op_sel_hi:[1,0]
	v_cvt_pk_bf16_f32 v66, v115, v115
	v_mfma_f32_16x16x32_bf16 v[44:47], v[174:177], v[118:121], v[44:47]
	global_store_short_d16_hi v[96:97], v66, off offset:160
	v_cvt_pk_bf16_f32 v66, v108, v108
	v_mfma_f32_16x16x32_bf16 v[52:55], v[174:177], v[150:153], v[52:55]
	global_store_short_d16_hi v[64:65], v66, off offset:128
	v_cvt_pk_bf16_f32 v66, v116, v116
	v_mfma_f32_16x16x32_bf16 v[56:59], v[174:177], v[162:165], v[56:59]
	global_store_short_d16_hi v[64:65], v66, off offset:160
	v_cvt_pk_bf16_f32 v64, v109, v109
	v_mfma_f32_16x16x32_bf16 v[60:63], v[174:177], v[178:181], v[60:63]
	global_store_short_d16_hi v[68:69], v64, off offset:128
	v_cvt_pk_bf16_f32 v64, v117, v117
	v_mfma_f32_16x16x32_bf16 v[48:51], v[154:157], v[158:161], v[48:51]
	global_store_short_d16_hi v[68:69], v64, off offset:160
	v_mfma_f32_16x16x32_bf16 v[32:35], v[154:157], v[170:173], v[32:35]
	s_waitcnt lgkmcnt(2)
	v_mfma_f32_16x16x32_bf16 v[36:39], v[154:157], v[182:185], v[36:39]
	s_waitcnt lgkmcnt(1)
	v_mfma_f32_16x16x32_bf16 v[28:31], v[154:157], v[186:189], v[28:31]
	s_waitcnt lgkmcnt(0)
	v_mfma_f32_16x16x32_bf16 v[44:47], v[98:101], v[158:161], v[44:47]
	v_mfma_f32_16x16x32_bf16 v[52:55], v[98:101], v[170:173], v[52:55]
	v_mfma_f32_16x16x32_bf16 v[56:59], v[98:101], v[182:185], v[56:59]
	v_mfma_f32_16x16x32_bf16 v[60:63], v[98:101], v[186:189], v[60:63]
	s_cbranch_scc0 .LBB0_332
